# attn sel/win loop unrolled x2 with accumulator register permutation: no per-step v_mov_b64 phi copies; copy A owns sync+DMA
# speedup vs baseline: 1.0110x; 1.0110x over previous
; #define AF_WAITV(n) asm volatile("s_waitcnt vmcnt(" #n ")" ::: "memory")
; #define AF_BAR() do { __builtin_amdgcn_s_barrier(); asm volatile("" ::: "memory"); } while (0)
; __device__ __forceinline__ void attn_fast(const Ptrs& P, LAS unsigned char* lds, int G, int bid) {
;     ...
;                 for (int i = 0; i < nt; ++i) {
;                     const int j = j_lo + i;
;                     if (i + 2 < nt) AF_WAITV(8); else if (i + 1 < nt) AF_WAITV(4); else AF_WAITV(0);
;                     AF_BAR();
;                     if (i + 3 < nt) AF_ISSUE((i + 3) & 3, KB, VB, DINP, 64 * (j + 3), true);
.LBB0_583:
	s_waitcnt vmcnt(0)
	s_barrier
	s_add_i32 s6, s3, 2
	s_cmp_gt_i32 s6, s17
	s_cbranch_scc1 .LBB0_590
	s_add_i32 s6, s16, 0x80
	s_mul_i32 s6, s6, 0x2e00
	s_add_u32 s6, s56, s6
	s_addc_u32 s7, s57, 0
	s_add_i32 s8, s23, 0x10000
	s_and_b32 s8, s8, 0x18000
	s_add_i32 s8, s76, s8
	s_mov_b32 m0, s8
	s_nop 0
	global_load_lds_dwordx4 v244, s[6:7]
	s_add_i32 m0, s8, 0x4000
	s_nop 0
	global_load_lds_dwordx4 v245, s[6:7]
	s_add_i32 m0, s8, 0x400
	s_nop 0
	global_load_lds_dwordx4 v246, s[6:7]
	s_add_i32 m0, s8, 0x4400
	s_nop 0
	global_load_lds_dwordx4 v247, s[6:7]
	s_add_i32 s6, s3, 3
	s_cmp_gt_i32 s6, s17
	s_cbranch_scc1 .LBB0_590
	s_add_i32 s6, s16, 0xc0
	s_mul_i32 s6, s6, 0x2e00
	s_add_u32 s6, s56, s6
	s_addc_u32 s7, s57, 0
	s_add_i32 s8, s23, 0x18000
	s_and_b32 s8, s8, 0x18000
	s_add_i32 s8, s76, s8
	s_mov_b32 m0, s8
	s_nop 0
	global_load_lds_dwordx4 v244, s[6:7]
	s_add_i32 m0, s8, 0x4000
	s_nop 0
	global_load_lds_dwordx4 v245, s[6:7]
	s_add_i32 m0, s8, 0x400
	s_nop 0
	global_load_lds_dwordx4 v246, s[6:7]
	s_add_i32 m0, s8, 0x4400
	s_nop 0
	global_load_lds_dwordx4 v247, s[6:7]

; #define LAS __attribute__((address_space(3)))
; #define AF_WAITV(n) asm volatile("s_waitcnt vmcnt(" #n ")" ::: "memory")
; #define AF_BAR() do { __builtin_amdgcn_s_barrier(); asm volatile("" ::: "memory"); } while (0)
; __device__ __forceinline__ void attn_fast(const Ptrs& P, LAS unsigned char* lds, int G, int bid) {
;     ...
; #pragma unroll 1
;                 for (int i = 0; i < nt; ++i) {
;                     const int j = j_lo + i;
;                     if (i + 2 < nt) AF_WAITV(8); else if (i + 1 < nt) AF_WAITV(4); else AF_WAITV(0);
;                     AF_BAR();
;                     if (i + 3 < nt) AF_ISSUE((i + 3) & 3, KB, VB, DINP, 64 * (j + 3), true);
;                     int hi[2], lo[2]; bool act[2];
;                     const bool needmask = (j == qb) || (br == 2 && 64 * j <= 64 * qb + 63 - 512);
; #pragma unroll
;                     for (int ct = 0; ct < 2; ++ct) {
;                         if (br == 1) { const unsigned wd = SELM[(8 * w + 4 * ct + qi) * 4 + (j >> 5)]; const bool bit = (wd >> (j & 31)) & 1u;
;                             act[ct] = __ballot(bit) != 0ull; hi[ct] = bit ? tq[ct] : -1; lo[ct] = NEGBIG; }
;                         else { act[ct] = true; hi[ct] = tq[ct]; lo[ct] = tq[ct] - 512; }
;                     }
;                     const LAS unsigned char* stg = lds + (i & 3) * 32768;
;                     if (act[0] && act[1]) af_tile_online<true, true>(stg, kl, vl0, vz, qf, s, m, l, o, needmask, 64 * j, fq, hi, lo, SC);
;                     else if (act[0])      af_tile_online<true, false>(stg, kl, vl0, vz, qf, s, m, l, o, needmask, 64 * j, fq, hi, lo, SC);
;                     else if (act[1])      af_tile_online<false, true>(stg, kl, vl0, vz, qf, s, m, l, o, needmask, 64 * j, fq, hi, lo, SC);
;                 }
.LBB0_619:
	s_add_i32 s3, s3, 1
	s_add_i32 s23, s23, 0x8000
	s_add_i32 s16, s16, 64
	s_cmp_eq_u32 s22, s3
	s_cbranch_scc1 .LBB0_623
	v_mov_b32_e32 v216, v223
	v_mov_b32_e32 v5, v222
	v_mov_b32_e32 v217, v221
	v_mov_b32_e32 v4, v224
	s_branch .Lu2_583

; __device__ __forceinline__ void attn_fast(const Ptrs& P, LAS unsigned char* lds, int G, int bid) {
;     ...
;                     int hi[2], lo[2]; bool act[2];
;                     const bool needmask = (j == qb) || (br == 2 && 64 * j <= 64 * qb + 63 - 512);
; #pragma unroll
;                     for (int ct = 0; ct < 2; ++ct) {
;                         if (br == 1) { const unsigned wd = SELM[(8 * w + 4 * ct + qi) * 4 + (j >> 5)]; const bool bit = (wd >> (j & 31)) & 1u;
;                             act[ct] = __ballot(bit) != 0ull; hi[ct] = bit ? tq[ct] : -1; lo[ct] = NEGBIG; }
;                         else { act[ct] = true; hi[ct] = tq[ct]; lo[ct] = tq[ct] - 512; }
;                     }
.Lu2_583:
.Lu2_590:
	s_add_i32 s6, s67, s3
	s_ashr_i32 s7, s6, 5
	s_lshl_b32 s7, s7, 2
	s_add_i32 s7, s7, 0
	s_add_i32 s61, s7, 0x20400
	v_cndmask_b32_e64 v2, 0, 1, s[54:55]
	s_lshl_b32 s60, 1, s6
	s_mov_b64 s[8:9], -1
	v_cmp_ne_u32_e64 s[6:7], 1, v2
	s_andn2_b64 vcc, exec, s[54:55]
	v_add_u32_e32 v94, s61, v186
	v_mov_b32_e32 v219, v208
	v_mov_b32_e32 v220, v212
	s_mov_b64 s[62:63], -1
	s_cbranch_vccnz .Lu2_592
	s_and_b32 s61, s3, 31
	s_cmp_lg_u32 s61, 0
	s_cbranch_scc1 .Lu2_have
	ds_read_b32 v248, v94
	ds_read_b32 v249, v94 offset:64
	s_waitcnt lgkmcnt(0)

; #define LAS __attribute__((address_space(3)))
; template <bool a0, bool a1> __device__ __forceinline__ void af_qk(const LAS unsigned char* kbuf, const unsigned (&kl)[4], const half8 (&qf)[2][4], f32x4 (&s)[2][4]) {
;     const LAS unsigned char* ka[4];
;     { int _ln; asm volatile("v_mov_b32 %0, %1" : "=v"(_ln) : "v"(kl[0]));
;       const int fr_ = _ln & 15, e_ = (_ln >> 4) ^ fr_;
; #pragma unroll
;       for (int ks = 0; ks < 4; ++ks) ka[ks] = kbuf + fr_ * 256 + ((e_ ^ (4 * ks)) << 4); }
;     half8 kf[2][4];
; #pragma unroll
;     for (int ks = 0; ks < 4; ++ks) kf[0][ks] = *(const LAS half8*)(ka[ks]);
; #pragma unroll
;     for (int kt = 0; kt < 4; ++kt) {
;         if (kt < 3) {
; #pragma unroll
;             for (int ks = 0; ks < 4; ++ks) kf[(kt + 1) & 1][ks] = *(const LAS half8*)(ka[ks] + (kt + 1) * 4096); }
;         s[0][kt] = (f32x4){0.f, 0.f, 0.f, 0.f}; s[1][kt] = (f32x4){0.f, 0.f, 0.f, 0.f};
; #pragma unroll
;         for (int ks = 0; ks < 4; ++ks) {
;             if (a0) s[0][kt] = __builtin_amdgcn_mfma_f32_16x16x32_f16(kf[kt & 1][ks], qf[0][ks], s[0][kt], 0, 0, 0);
;             if (a1) s[1][kt] = __builtin_amdgcn_mfma_f32_16x16x32_f16(kf[kt & 1][ks], qf[1][ks], s[1][kt], 0, 0, 0); }
;         __builtin_amdgcn_sched_barrier(0);
;     }
; __device__ __forceinline__ void af_maskraw(f32x4 (&s)[4], int mbase, int mstep, int fq, int hi, int lo) {
; #pragma unroll
;     for (int kt = 0; kt < 4; ++kt)
; #pragma unroll
;         for (int jj = 0; jj < 4; ++jj) { const int met = mbase + mstep * (16 * kt + 4 * fq + jj); s[kt][jj] = (met <= hi && met > lo) ? s[kt][jj] : -3.0e38f; }
; }
.Lu2_594:
	s_cmp_eq_u32 s17, s3
	s_cselect_b64 s[6:7], -1, 0
	s_cmp_le_i32 s16, s97
	s_cselect_b64 s[60:61], -1, 0
	s_and_b64 s[60:61], s[12:13], s[60:61]
	s_or_b64 s[60:61], s[6:7], s[60:61]
	s_and_b32 s6, s23, 0x18000
	s_add_i32 s64, s6, 0
	s_and_b64 s[6:7], s[62:63], s[8:9]
	s_andn2_b64 vcc, exec, s[6:7]
	s_mov_b64 s[6:7], -1
	s_cbranch_vccz .Lu2_610
	s_xor_b64 s[62:63], s[62:63], -1
	s_and_b64 vcc, exec, s[62:63]
	s_cbranch_vccz .Lu2_603
	v_mov_b64_e32 v[48:49], v[132:133]
	v_mov_b64_e32 v[52:53], v[128:129]
	v_mov_b64_e32 v[64:65], v[124:125]
	v_mov_b64_e32 v[68:69], v[120:121]
	v_mov_b64_e32 v[76:77], v[116:117]
	v_mov_b64_e32 v[84:85], v[112:113]
	v_mov_b64_e32 v[88:89], v[108:109]
	v_mov_b64_e32 v[96:97], v[104:105]
	s_andn2_b64 vcc, exec, s[8:9]
	v_mov_b32_e32 v224, v4
	v_mov_b32_e32 v222, v5
	v_mov_b64_e32 v[46:47], v[130:131]
	v_mov_b64_e32 v[50:51], v[126:127]
	v_mov_b64_e32 v[62:63], v[122:123]
	v_mov_b64_e32 v[66:67], v[118:119]
	v_mov_b64_e32 v[74:75], v[114:115]
	v_mov_b64_e32 v[82:83], v[110:111]
	v_mov_b64_e32 v[86:87], v[106:107]
	v_mov_b64_e32 v[94:95], v[102:103]
	s_cbranch_vccnz .Lu2_602
	v_mov_b32 v94, v172
	s_nop 0
	v_and_b32_e32 v95, 15, v94
	v_lshl_add_u32 v74, v95, 8, s64
	v_lshlrev_b32_e32 v95, 4, v95
	v_bitop3_b32 v75, v95, v94, -16 bitop3:0x78
	v_add_u32_e32 v98, v74, v75
	ds_read_b128 v[94:97], v98
	ds_read_b128 v[86:89], v98 offset:4096
	v_xad_u32 v99, v75, 64, v74
	ds_read_b128 v[82:85], v99
	ds_read_b128 v[66:69], v99 offset:4096
	v_xad_u32 v100, v75, s77, v74
	s_waitcnt lgkmcnt(0)
	v_mfma_f32_16x16x32_f16 v[94:97], v[94:97], v[22:25], 0
	v_xad_u32 v101, v75, s78, v74
	ds_read_b128 v[62:65], v100 offset:4096
	v_mfma_f32_16x16x32_f16 v[94:97], v[82:85], v[26:29], v[94:97]
	ds_read_b128 v[82:85], v100
	s_waitcnt lgkmcnt(0)
	v_mfma_f32_16x16x32_f16 v[94:97], v[82:85], v[30:33], v[94:97]
	ds_read_b128 v[82:85], v101
	ds_read_b128 v[50:53], v101 offset:4096
	s_waitcnt lgkmcnt(0)
	v_mfma_f32_16x16x32_f16 v[74:77], v[82:85], v[34:37], v[94:97]
	v_mfma_f32_16x16x32_f16 v[94:97], v[86:89], v[22:25], 0
	v_mfma_f32_16x16x32_f16 v[94:97], v[66:69], v[26:29], v[94:97]
	v_mfma_f32_16x16x32_f16 v[94:97], v[62:65], v[30:33], v[94:97]
	ds_read_b128 v[86:89], v98 offset:8192
	ds_read_b128 v[66:69], v99 offset:8192
	ds_read_b128 v[62:65], v100 offset:8192
	ds_read_b128 v[46:49], v101 offset:8192
	v_mfma_f32_16x16x32_f16 v[82:85], v[50:53], v[34:37], v[94:97]
	s_waitcnt lgkmcnt(0)
	v_mfma_f32_16x16x32_f16 v[94:97], v[86:89], v[22:25], 0
	v_mfma_f32_16x16x32_f16 v[94:97], v[66:69], v[26:29], v[94:97]
	v_mfma_f32_16x16x32_f16 v[94:97], v[62:65], v[30:33], v[94:97]
	ds_read_b128 v[66:69], v98 offset:12288
	ds_read_b128 v[62:65], v99 offset:12288
	ds_read_b128 v[50:53], v100 offset:12288
	ds_read_b128 v[98:101], v101 offset:12288
	v_mfma_f32_16x16x32_f16 v[86:89], v[46:49], v[34:37], v[94:97]
	s_waitcnt lgkmcnt(0)
	v_mfma_f32_16x16x32_f16 v[94:97], v[66:69], v[22:25], 0
	v_mfma_f32_16x16x32_f16 v[94:97], v[62:65], v[26:29], v[94:97]
	v_mfma_f32_16x16x32_f16 v[94:97], v[50:53], v[30:33], v[94:97]
	v_mfma_f32_16x16x32_f16 v[94:97], v[98:101], v[34:37], v[94:97]
	s_andn2_b64 vcc, exec, s[60:61]
	s_cbranch_vccnz .Lu2_599
	v_add_u32_e32 v66, s16, v173
	v_cmp_le_i32_e32 vcc, v66, v2
	v_cmp_gt_i32_e64 s[6:7], v66, v218
	s_and_b64 vcc, vcc, s[6:7]
	v_cndmask_b32_e32 v74, v202, v74, vcc
	v_cmp_lt_i32_e32 vcc, v66, v2
	v_cmp_ge_i32_e64 s[6:7], v66, v218
	s_and_b64 vcc, vcc, s[6:7]
	v_add_u32_e32 v67, 2, v66
	v_cndmask_b32_e32 v75, v202, v75, vcc
	v_cmp_le_i32_e32 vcc, v67, v2
	v_cmp_gt_i32_e64 s[6:7], v67, v218
	s_and_b64 vcc, vcc, s[6:7]
	v_add_u32_e32 v67, 3, v66
	v_cndmask_b32_e32 v76, v202, v76, vcc
	v_cmp_le_i32_e32 vcc, v67, v2
	v_cmp_gt_i32_e64 s[6:7], v67, v218
	s_and_b64 vcc, vcc, s[6:7]
	v_add_u32_e32 v67, 16, v66
	v_cndmask_b32_e32 v77, v202, v77, vcc
	v_cmp_le_i32_e32 vcc, v67, v2
	v_cmp_gt_i32_e64 s[6:7], v67, v218
	s_and_b64 vcc, vcc, s[6:7]
	v_add_u32_e32 v67, 17, v66
	v_cndmask_b32_e32 v82, v202, v82, vcc
	v_cmp_le_i32_e32 vcc, v67, v2
	v_cmp_gt_i32_e64 s[6:7], v67, v218
	s_and_b64 vcc, vcc, s[6:7]
	v_add_u32_e32 v67, 18, v66
	v_cndmask_b32_e32 v83, v202, v83, vcc
	v_cmp_le_i32_e32 vcc, v67, v2
	v_cmp_gt_i32_e64 s[6:7], v67, v218
	s_and_b64 vcc, vcc, s[6:7]
	v_add_u32_e32 v67, 19, v66
	v_cndmask_b32_e32 v84, v202, v84, vcc
	v_cmp_le_i32_e32 vcc, v67, v2
	v_cmp_gt_i32_e64 s[6:7], v67, v218
	s_and_b64 vcc, vcc, s[6:7]
	v_add_u32_e32 v67, 32, v66
	v_cndmask_b32_e32 v85, v202, v85, vcc
	v_cmp_le_i32_e32 vcc, v67, v2
	v_cmp_gt_i32_e64 s[6:7], v67, v218
	s_and_b64 vcc, vcc, s[6:7]
	v_add_u32_e32 v67, 33, v66
	v_cndmask_b32_e32 v86, v202, v86, vcc
	v_cmp_le_i32_e32 vcc, v67, v2
	v_cmp_gt_i32_e64 s[6:7], v67, v218
	s_and_b64 vcc, vcc, s[6:7]
	v_add_u32_e32 v67, 34, v66
	v_cndmask_b32_e32 v87, v202, v87, vcc
	v_cmp_le_i32_e32 vcc, v67, v2
	v_cmp_gt_i32_e64 s[6:7], v67, v218
	s_and_b64 vcc, vcc, s[6:7]
	v_add_u32_e32 v67, 35, v66
	v_cndmask_b32_e32 v88, v202, v88, vcc
	v_cmp_le_i32_e32 vcc, v67, v2
	v_cmp_gt_i32_e64 s[6:7], v67, v218
	s_and_b64 vcc, vcc, s[6:7]
	v_add_u32_e32 v67, 48, v66
	v_cndmask_b32_e32 v89, v202, v89, vcc
	v_cmp_le_i32_e32 vcc, v67, v2
	v_cmp_gt_i32_e64 s[6:7], v67, v218
	s_and_b64 vcc, vcc, s[6:7]
	v_add_u32_e32 v67, 49, v66
	v_cndmask_b32_e32 v94, v202, v94, vcc
	v_cmp_le_i32_e32 vcc, v67, v2
	v_cmp_gt_i32_e64 s[6:7], v67, v218
	s_and_b64 vcc, vcc, s[6:7]
	v_add_u32_e32 v67, 50, v66
	v_cndmask_b32_e32 v95, v202, v95, vcc
	v_cmp_le_i32_e32 vcc, v67, v2
	v_cmp_gt_i32_e64 s[6:7], v67, v218
	s_and_b64 vcc, vcc, s[6:7]
	v_add_u32_e32 v66, 51, v66
	v_cndmask_b32_e32 v96, v202, v96, vcc
	v_cmp_le_i32_e32 vcc, v66, v2
	v_cmp_gt_i32_e64 s[6:7], v66, v218
	s_and_b64 vcc, vcc, s[6:7]
	v_cndmask_b32_e32 v97, v202, v97, vcc
; __device__ __forceinline__ void af_online_fast(f32x4 (&s)[4], bool colsel, float& m, float& l, f32x4 (&o)[8], half8 (&pf)[2], float SC) {
;     float lm = fmaxf(fmaxf(s[0][0], s[0][1]), fmaxf(s[0][2], s[0][3]));
; #pragma unroll
;     for (int kt = 1; kt < 4; ++kt) lm = fmaxf(lm, fmaxf(fmaxf(s[kt][0], s[kt][1]), fmaxf(s[kt][2], s[kt][3])));
;     if (__ballot(colsel && (lm * SC > m + 8.f)) != 0ull) {
;         float v = lm; v = fmaxf(v, __shfl_xor(v, 16)); v = fmaxf(v, __shfl_xor(v, 32));
;         const float mloc = colsel ? v * SC : -1.0e30f;
;         const float mn = fmaxf(m, mloc); const float al = __builtin_amdgcn_exp2f(m - mn); m = mn;
;         l *= al;
; #pragma unroll
;         for (int dt = 0; dt < 8; ++dt) o[dt] *= al;
;     }
.Lu2_599:
	v_max_f32_e32 v66, v75, v75
	v_max_f32_e32 v67, v74, v74
	v_max_f32_e32 v66, v67, v66
	v_max_f32_e32 v67, v77, v77
	v_max_f32_e32 v68, v76, v76
	v_max_f32_e32 v67, v68, v67
	v_max_f32_e32 v68, v85, v85
	v_max_f32_e32 v69, v84, v84
	v_max_f32_e32 v68, v69, v68
	v_max3_f32 v68, v82, v83, v68
	v_max3_f32 v66, v66, v67, v68
	v_max_f32_e32 v67, v89, v89
	v_max_f32_e32 v68, v88, v88
	v_max_f32_e32 v67, v68, v67
	v_max_f32_e32 v68, v97, v97
	v_max_f32_e32 v69, v96, v96
	v_max_f32_e32 v68, v69, v68
	v_max3_f32 v67, v86, v87, v67
	v_max3_f32 v68, v94, v95, v68
	v_max3_f32 v59, v66, v67, v68
	v_mul_f32_e32 v66, 0x3e0293ee, v59
	v_add_f32_e32 v67, 0x41000000, v4
	v_cmp_lt_i32_e64 s[6:7], -1, v2
	v_cmp_gt_f32_e32 vcc, v66, v67
	v_mov_b64_e32 v[72:73], v[104:105]
	v_mov_b64_e32 v[80:81], v[108:109]
	v_mov_b64_e32 v[100:101], v[112:113]
	v_mov_b64_e32 v[92:93], v[116:117]
	v_mov_b64_e32 v[68:69], v[120:121]
	v_mov_b64_e32 v[64:65], v[124:125]
	v_mov_b64_e32 v[52:53], v[128:129]
	v_mov_b64_e32 v[48:49], v[132:133]
	s_and_b64 vcc, s[6:7], vcc
	v_mov_b64_e32 v[70:71], v[102:103]
	v_mov_b64_e32 v[78:79], v[106:107]
	v_mov_b64_e32 v[98:99], v[110:111]
	v_mov_b64_e32 v[90:91], v[114:115]
	v_mov_b64_e32 v[66:67], v[118:119]
	v_mov_b64_e32 v[62:63], v[122:123]
	v_mov_b64_e32 v[50:51], v[126:127]
	v_mov_b64_e32 v[46:47], v[130:131]
	v_mov_b32_e32 v58, v5
	v_mov_b32_e32 v224, v4
	s_cbranch_vccz .Lu2_601
	ds_bpermute_b32 v66, v167, v59
	v_max_f32_e32 v67, v59, v59
	v_max_f32_e32 v68, v4, v4
	s_waitcnt lgkmcnt(0)
	v_max_f32_e32 v66, v66, v66
	v_max_f32_e32 v66, v67, v66
	ds_bpermute_b32 v67, v207, v66
	s_waitcnt lgkmcnt(0)
	v_max_f32_e32 v67, v67, v67
	v_max_f32_e32 v66, v66, v67
	v_mul_f32_e32 v66, 0x3e0293ee, v66
	v_cndmask_b32_e64 v66, v206, v66, s[6:7]
	v_max_f32_e32 v224, v68, v66
	v_sub_f32_e32 v66, v4, v224
	v_exp_f32_e32 v46, v66
	s_nop 0
	v_mul_f32_e32 v58, v5, v46
	v_pk_mul_f32 v[72:73], v[104:105], v[46:47] op_sel_hi:[1,0]
	v_pk_mul_f32 v[70:71], v[102:103], v[46:47] op_sel_hi:[1,0]
	v_pk_mul_f32 v[80:81], v[108:109], v[46:47] op_sel_hi:[1,0]
	v_pk_mul_f32 v[78:79], v[106:107], v[46:47] op_sel_hi:[1,0]
	v_pk_mul_f32 v[100:101], v[112:113], v[46:47] op_sel_hi:[1,0]
	v_pk_mul_f32 v[98:99], v[110:111], v[46:47] op_sel_hi:[1,0]
	v_pk_mul_f32 v[92:93], v[116:117], v[46:47] op_sel_hi:[1,0]
	v_pk_mul_f32 v[90:91], v[114:115], v[46:47] op_sel_hi:[1,0]
	v_pk_mul_f32 v[68:69], v[120:121], v[46:47] op_sel_hi:[1,0]
	v_pk_mul_f32 v[66:67], v[118:119], v[46:47] op_sel_hi:[1,0]
	v_pk_mul_f32 v[64:65], v[124:125], v[46:47] op_sel_hi:[1,0]
	v_pk_mul_f32 v[62:63], v[122:123], v[46:47] op_sel_hi:[1,0]
	v_pk_mul_f32 v[52:53], v[128:129], v[46:47] op_sel_hi:[1,0]
	v_pk_mul_f32 v[50:51], v[126:127], v[46:47] op_sel_hi:[1,0]
	v_pk_mul_f32 v[48:49], v[132:133], v[46:47] op_sel_hi:[1,0]
	v_pk_mul_f32 v[46:47], v[130:131], v[46:47] op_sel_hi:[1,0]
; #define LAS __attribute__((address_space(3)))
; #define AF_VWAIT(buf_, n_) asm volatile("s_waitcnt lgkmcnt(" #n_ ")" : "+v"(vr[buf_][0]), "+v"(vr[buf_][1]), "+v"(vr[buf_][2]), "+v"(vr[buf_][3]), "+v"(vr[buf_][4]), "+v"(vr[buf_][5]), "+v"(vr[buf_][6]), "+v"(vr[buf_][7]) :: "memory")
; template <bool a0, bool a1> __device__ __forceinline__ void af_pv(const LAS unsigned char* vbuf, unsigned vl0, int z, const half8 (&pf)[2][2], f32x4 (&o)[2][8]) {
;     const unsigned rb = (unsigned)(__UINTPTR_TYPE__)(vbuf + vl0);
;     s16x4 vr[2][8];
;     ...
;     AF_VLOAD(0, 0); AF_VLOAD(1, 2);
;     AF_VWAIT(0, 8); AF_VMMA(0, 0); AF_VLOAD(0, 4);
;     AF_VWAIT(1, 8); AF_VMMA(1, 2); AF_VLOAD(1, 6);
;     AF_VWAIT(0, 8); AF_VMMA(0, 4);
;     AF_VWAIT(1, 0); AF_VMMA(1, 6);
; __device__ __forceinline__ void af_online_fast(f32x4 (&s)[4], bool colsel, float& m, float& l, f32x4 (&o)[8], half8 (&pf)[2], float SC) {
;     ...
;     const float bias = colsel ? -m : -1.0e30f; float ps = 0.f;
; #pragma unroll
;     for (int kt = 0; kt < 4; ++kt)
; #pragma unroll
;         for (int jj = 0; jj < 4; ++jj) { const float p = __builtin_amdgcn_exp2f(__builtin_fmaf(s[kt][jj], SC, bias)); s[kt][jj] = p; ps += p; }
;     l += ps;
;     af_pack(s, pf);
; }
.Lu2_601:
	v_cndmask_b32_e64 v59, v206, -v224, s[6:7]
	v_fmamk_f32 v74, v74, 0x3e0293ee, v59
	v_exp_f32_e32 v221, v74
	v_fmamk_f32 v75, v75, 0x3e0293ee, v59
	v_exp_f32_e32 v223, v75
	v_fmamk_f32 v75, v76, 0x3e0293ee, v59
	v_exp_f32_e32 v225, v75
	v_fmamk_f32 v75, v77, 0x3e0293ee, v59
	v_exp_f32_e32 v226, v75
	v_fmamk_f32 v82, v82, 0x3e0293ee, v59
	v_add_f32_e32 v74, 0, v221
	v_exp_f32_e32 v227, v82
	v_fmamk_f32 v83, v83, 0x3e0293ee, v59
	v_add_f32_e32 v74, v223, v74
	v_exp_f32_e32 v228, v83
	v_fmamk_f32 v83, v84, 0x3e0293ee, v59
	v_add_f32_e32 v74, v225, v74
	v_exp_f32_e32 v229, v83
	v_fmamk_f32 v83, v85, 0x3e0293ee, v59
	v_add_f32_e32 v74, v226, v74
	v_exp_f32_e32 v230, v83
	v_fmamk_f32 v86, v86, 0x3e0293ee, v59
	v_add_f32_e32 v82, v227, v74
	v_exp_f32_e32 v231, v86
	v_fmamk_f32 v87, v87, 0x3e0293ee, v59
	v_add_f32_e32 v82, v228, v82
	v_exp_f32_e32 v232, v87
	v_fmamk_f32 v87, v88, 0x3e0293ee, v59
	v_add_f32_e32 v82, v229, v82
	v_exp_f32_e32 v233, v87
	v_fmamk_f32 v87, v89, 0x3e0293ee, v59
	v_add_f32_e32 v82, v230, v82
	v_exp_f32_e32 v234, v87
	v_fmamk_f32 v94, v94, 0x3e0293ee, v59
	v_add_f32_e32 v86, v231, v82
	v_exp_f32_e32 v235, v94
	v_fmamk_f32 v95, v95, 0x3e0293ee, v59
	v_add_f32_e32 v86, v232, v86
	v_exp_f32_e32 v236, v95
	v_fmamk_f32 v95, v96, 0x3e0293ee, v59
	v_add_f32_e32 v86, v233, v86
	v_exp_f32_e32 v237, v95
	v_fmac_f32_e32 v59, 0x3e0293ee, v97
	v_add_f32_e32 v86, v234, v86
	v_exp_f32_e32 v238, v59
	v_add_f32_e32 v94, v235, v86
	v_add_f32_e32 v94, v236, v94
	v_add_f32_e32 v94, v237, v94
	v_add_f32_e32 v94, v238, v94
	v_add_f32_e32 v222, v58, v94
	v_add_u32_e32 v94, s64, v174
	v_add_u32_e32 v242, 0x4000, v94
	v_add_u32_e32 v58, v177, v242
	v_add_u32_e32 v59, v178, v242
	ds_read_b64_tr_b16 v[74:75], v58
	ds_read_b64_tr_b16 v[76:77], v58 offset:4096
	ds_read_b64_tr_b16 v[94:95], v58 offset:8192
	ds_read_b64_tr_b16 v[96:97], v58 offset:12288
	ds_read_b64_tr_b16 v[82:83], v59
	ds_read_b64_tr_b16 v[84:85], v59 offset:4096
	ds_read_b64_tr_b16 v[86:87], v59 offset:8192
	ds_read_b64_tr_b16 v[88:89], v59 offset:12288
	v_add_u32_e32 v239, v179, v242
	v_add_u32_e32 v240, v180, v242
	ds_read_b64_tr_b16 v[38:39], v239
	ds_read_b64_tr_b16 v[40:41], v239 offset:4096
	ds_read_b64_tr_b16 v[42:43], v239 offset:8192
	ds_read_b64_tr_b16 v[44:45], v239 offset:12288
	ds_read_b64_tr_b16 v[54:55], v240
	ds_read_b64_tr_b16 v[56:57], v240 offset:4096
	ds_read_b64_tr_b16 v[58:59], v240 offset:8192
	ds_read_b64_tr_b16 v[60:61], v240 offset:12288
	s_waitcnt lgkmcnt(8)
	v_cvt_pk_f16_f32 v229, v229, v230
	v_cvt_pk_f16_f32 v228, v227, v228
	v_cvt_pk_f16_f32 v227, v225, v226
	v_cvt_pk_f16_f32 v226, v221, v223
	s_nop 1
	v_mfma_f32_16x16x32_f16 v[74:77], v[74:77], v[226:229], v[70:73]
	v_mfma_f32_16x16x32_f16 v[82:85], v[82:85], v[226:229], v[78:81]
	s_nop 1
	v_cvt_pk_f16_f32 v73, v237, v238
	v_cvt_pk_f16_f32 v72, v235, v236
	v_cvt_pk_f16_f32 v71, v233, v234
	v_cvt_pk_f16_f32 v70, v231, v232
	s_nop 1
	v_mfma_f32_16x16x32_f16 v[94:97], v[94:97], v[70:73], v[74:77]
	v_mfma_f32_16x16x32_f16 v[86:89], v[86:89], v[70:73], v[82:85]
	s_nop 2
	v_add_u32_e32 v82, v181, v242
	v_add_u32_e32 v83, v182, v242
	ds_read_b64_tr_b16 v[238:239], v82
	ds_read_b64_tr_b16 v[240:241], v82 offset:4096
	ds_read_b64_tr_b16 v[234:235], v82 offset:8192
	ds_read_b64_tr_b16 v[236:237], v82 offset:12288
	ds_read_b64_tr_b16 v[230:231], v83
	ds_read_b64_tr_b16 v[232:233], v83 offset:4096
	ds_read_b64_tr_b16 v[78:79], v83 offset:8192
	ds_read_b64_tr_b16 v[80:81], v83 offset:12288
	s_waitcnt lgkmcnt(8)
	s_nop 0
	v_mfma_f32_16x16x32_f16 v[82:85], v[38:41], v[226:229], v[98:101]
	v_mfma_f32_16x16x32_f16 v[74:77], v[54:57], v[226:229], v[90:93]
	v_mfma_f32_16x16x32_f16 v[82:85], v[42:45], v[70:73], v[82:85]
	v_mfma_f32_16x16x32_f16 v[74:77], v[58:61], v[70:73], v[74:77]
	v_add_u32_e32 v42, v183, v242
	v_add_u32_e32 v43, v184, v242
	ds_read_b64_tr_b16 v[54:55], v42
	ds_read_b64_tr_b16 v[56:57], v42 offset:4096
	ds_read_b64_tr_b16 v[58:59], v42 offset:8192
	ds_read_b64_tr_b16 v[60:61], v42 offset:12288
	ds_read_b64_tr_b16 v[90:91], v43
	ds_read_b64_tr_b16 v[92:93], v43 offset:4096
	ds_read_b64_tr_b16 v[98:99], v43 offset:8192
	ds_read_b64_tr_b16 v[100:101], v43 offset:12288
	s_waitcnt lgkmcnt(8)
	s_nop 0
	v_mfma_f32_16x16x32_f16 v[66:69], v[238:241], v[226:229], v[66:69]
	v_mfma_f32_16x16x32_f16 v[62:65], v[230:233], v[226:229], v[62:65]
	v_mfma_f32_16x16x32_f16 v[66:69], v[234:237], v[70:73], v[66:69]
	v_mfma_f32_16x16x32_f16 v[62:65], v[78:81], v[70:73], v[62:65]
	s_waitcnt lgkmcnt(0)
	s_nop 0
	v_mfma_f32_16x16x32_f16 v[50:53], v[54:57], v[226:229], v[50:53]
	v_mfma_f32_16x16x32_f16 v[46:49], v[90:93], v[226:229], v[46:49]
	v_mfma_f32_16x16x32_f16 v[50:53], v[58:61], v[70:73], v[50:53]
	v_mfma_f32_16x16x32_f16 v[46:49], v[98:101], v[70:73], v[46:49]

; #define LAS __attribute__((address_space(3)))
; template <bool a0, bool a1> __device__ __forceinline__ void af_qk(const LAS unsigned char* kbuf, const unsigned (&kl)[4], const half8 (&qf)[2][4], f32x4 (&s)[2][4]) {
;     const LAS unsigned char* ka[4];
;     { int _ln; asm volatile("v_mov_b32 %0, %1" : "=v"(_ln) : "v"(kl[0]));
;       const int fr_ = _ln & 15, e_ = (_ln >> 4) ^ fr_;
; #pragma unroll
;       for (int ks = 0; ks < 4; ++ks) ka[ks] = kbuf + fr_ * 256 + ((e_ ^ (4 * ks)) << 4); }
;     half8 kf[2][4];
; #pragma unroll
;     for (int ks = 0; ks < 4; ++ks) kf[0][ks] = *(const LAS half8*)(ka[ks]);
; #pragma unroll
;     for (int kt = 0; kt < 4; ++kt) {
;         if (kt < 3) {
; #pragma unroll
;             for (int ks = 0; ks < 4; ++ks) kf[(kt + 1) & 1][ks] = *(const LAS half8*)(ka[ks] + (kt + 1) * 4096); }
;         s[0][kt] = (f32x4){0.f, 0.f, 0.f, 0.f}; s[1][kt] = (f32x4){0.f, 0.f, 0.f, 0.f};
; #pragma unroll
;         for (int ks = 0; ks < 4; ++ks) {
;             if (a0) s[0][kt] = __builtin_amdgcn_mfma_f32_16x16x32_f16(kf[kt & 1][ks], qf[0][ks], s[0][kt], 0, 0, 0);
;             if (a1) s[1][kt] = __builtin_amdgcn_mfma_f32_16x16x32_f16(kf[kt & 1][ks], qf[1][ks], s[1][kt], 0, 0, 0); }
;         __builtin_amdgcn_sched_barrier(0);
;     }
; __device__ __forceinline__ void af_maskraw(f32x4 (&s)[4], int mbase, int mstep, int fq, int hi, int lo) {
; #pragma unroll
;     for (int kt = 0; kt < 4; ++kt)
; #pragma unroll
;         for (int jj = 0; jj < 4; ++jj) { const int met = mbase + mstep * (16 * kt + 4 * fq + jj); s[kt][jj] = (met <= hi && met > lo) ? s[kt][jj] : -3.0e38f; }
; }
.Lu2_603:
	v_mov_b64_e32 v[100:101], v[136:137]
	v_mov_b64_e32 v[92:93], v[140:141]
	v_mov_b64_e32 v[80:81], v[144:145]
	v_mov_b64_e32 v[72:73], v[148:149]
	v_mov_b64_e32 v[60:61], v[152:153]
	v_mov_b64_e32 v[56:57], v[156:157]
	v_mov_b64_e32 v[44:45], v[160:161]
	v_mov_b64_e32 v[40:41], v[164:165]
	s_andn2_b64 vcc, exec, s[6:7]
	v_mov_b32_e32 v221, v217
	v_mov_b32_e32 v223, v216
	v_mov_b64_e32 v[98:99], v[134:135]
	v_mov_b64_e32 v[90:91], v[138:139]
	v_mov_b64_e32 v[78:79], v[142:143]
	v_mov_b64_e32 v[70:71], v[146:147]
	v_mov_b64_e32 v[58:59], v[150:151]
	v_mov_b64_e32 v[54:55], v[154:155]
	v_mov_b64_e32 v[42:43], v[158:159]
	v_mov_b64_e32 v[38:39], v[162:163]
	s_cbranch_vccnz .Lu2_609
	v_mov_b32 v94, v172
	s_nop 0
	v_and_b32_e32 v95, 15, v94
	v_lshl_add_u32 v66, v95, 8, s64
	v_lshlrev_b32_e32 v95, 4, v95
	v_bitop3_b32 v67, v95, v94, -16 bitop3:0x78
	v_add_u32_e32 v98, v66, v67
	ds_read_b128 v[94:97], v98
	ds_read_b128 v[86:89], v98 offset:4096
	v_xad_u32 v99, v67, 64, v66
	ds_read_b128 v[82:85], v99
	ds_read_b128 v[74:77], v99 offset:4096
	v_xad_u32 v100, v67, s77, v66
	s_waitcnt lgkmcnt(0)
	v_mfma_f32_16x16x32_f16 v[94:97], v[94:97], v[6:9], 0
	v_xad_u32 v101, v67, s78, v66
	ds_read_b128 v[66:69], v100 offset:4096
	v_mfma_f32_16x16x32_f16 v[94:97], v[82:85], v[10:13], v[94:97]
	ds_read_b128 v[82:85], v100
	s_waitcnt lgkmcnt(0)
	v_mfma_f32_16x16x32_f16 v[94:97], v[82:85], v[14:17], v[94:97]
	ds_read_b128 v[82:85], v101
	ds_read_b128 v[50:53], v101 offset:4096
	s_waitcnt lgkmcnt(0)
	v_mfma_f32_16x16x32_f16 v[62:65], v[82:85], v[18:21], v[94:97]
	v_mfma_f32_16x16x32_f16 v[94:97], v[86:89], v[6:9], 0
	v_mfma_f32_16x16x32_f16 v[94:97], v[74:77], v[10:13], v[94:97]
	v_mfma_f32_16x16x32_f16 v[94:97], v[66:69], v[14:17], v[94:97]
	ds_read_b128 v[86:89], v98 offset:8192
	ds_read_b128 v[74:77], v99 offset:8192
	ds_read_b128 v[66:69], v100 offset:8192
	ds_read_b128 v[46:49], v101 offset:8192
	v_mfma_f32_16x16x32_f16 v[82:85], v[50:53], v[18:21], v[94:97]
	s_waitcnt lgkmcnt(0)
	v_mfma_f32_16x16x32_f16 v[94:97], v[86:89], v[6:9], 0
	v_mfma_f32_16x16x32_f16 v[94:97], v[74:77], v[10:13], v[94:97]
	v_mfma_f32_16x16x32_f16 v[94:97], v[66:69], v[14:17], v[94:97]
	ds_read_b128 v[74:77], v98 offset:12288
	ds_read_b128 v[66:69], v99 offset:12288
	ds_read_b128 v[50:53], v100 offset:12288
	ds_read_b128 v[98:101], v101 offset:12288
	v_mfma_f32_16x16x32_f16 v[86:89], v[46:49], v[18:21], v[94:97]
	s_waitcnt lgkmcnt(0)
	v_mfma_f32_16x16x32_f16 v[94:97], v[74:77], v[6:9], 0
	v_mfma_f32_16x16x32_f16 v[94:97], v[66:69], v[10:13], v[94:97]
	v_mfma_f32_16x16x32_f16 v[94:97], v[50:53], v[14:17], v[94:97]
	v_mfma_f32_16x16x32_f16 v[94:97], v[98:101], v[18:21], v[94:97]
	s_andn2_b64 vcc, exec, s[60:61]
	s_cbranch_vccnz .Lu2_606
	v_add_u32_e32 v74, s16, v173
	v_cmp_le_i32_e32 vcc, v74, v219
	v_cmp_gt_i32_e64 s[6:7], v74, v220
	s_and_b64 vcc, vcc, s[6:7]
	v_cndmask_b32_e32 v62, v202, v62, vcc
	v_cmp_lt_i32_e32 vcc, v74, v219
	v_cmp_ge_i32_e64 s[6:7], v74, v220
	s_and_b64 vcc, vcc, s[6:7]
	v_add_u32_e32 v75, 2, v74
	v_cndmask_b32_e32 v63, v202, v63, vcc
	v_cmp_le_i32_e32 vcc, v75, v219
	v_cmp_gt_i32_e64 s[6:7], v75, v220
	s_and_b64 vcc, vcc, s[6:7]
	v_add_u32_e32 v75, 3, v74
	v_cndmask_b32_e32 v64, v202, v64, vcc
	v_cmp_le_i32_e32 vcc, v75, v219
	v_cmp_gt_i32_e64 s[6:7], v75, v220
	s_and_b64 vcc, vcc, s[6:7]
	v_add_u32_e32 v75, 16, v74
	v_cndmask_b32_e32 v65, v202, v65, vcc
	v_cmp_le_i32_e32 vcc, v75, v219
	v_cmp_gt_i32_e64 s[6:7], v75, v220
	s_and_b64 vcc, vcc, s[6:7]
	v_add_u32_e32 v75, 17, v74
	v_cndmask_b32_e32 v82, v202, v82, vcc
	v_cmp_le_i32_e32 vcc, v75, v219
	v_cmp_gt_i32_e64 s[6:7], v75, v220
	s_and_b64 vcc, vcc, s[6:7]
	v_add_u32_e32 v75, 18, v74
	v_cndmask_b32_e32 v83, v202, v83, vcc
	v_cmp_le_i32_e32 vcc, v75, v219
	v_cmp_gt_i32_e64 s[6:7], v75, v220
	s_and_b64 vcc, vcc, s[6:7]
	v_add_u32_e32 v75, 19, v74
	v_cndmask_b32_e32 v84, v202, v84, vcc
	v_cmp_le_i32_e32 vcc, v75, v219
	v_cmp_gt_i32_e64 s[6:7], v75, v220
	s_and_b64 vcc, vcc, s[6:7]
	v_add_u32_e32 v75, 32, v74
	v_cndmask_b32_e32 v85, v202, v85, vcc
	v_cmp_le_i32_e32 vcc, v75, v219
	v_cmp_gt_i32_e64 s[6:7], v75, v220
	s_and_b64 vcc, vcc, s[6:7]
	v_add_u32_e32 v75, 33, v74
	v_cndmask_b32_e32 v86, v202, v86, vcc
	v_cmp_le_i32_e32 vcc, v75, v219
	v_cmp_gt_i32_e64 s[6:7], v75, v220
	s_and_b64 vcc, vcc, s[6:7]
	v_add_u32_e32 v75, 34, v74
	v_cndmask_b32_e32 v87, v202, v87, vcc
	v_cmp_le_i32_e32 vcc, v75, v219
	v_cmp_gt_i32_e64 s[6:7], v75, v220
	s_and_b64 vcc, vcc, s[6:7]
	v_add_u32_e32 v75, 35, v74
	v_cndmask_b32_e32 v88, v202, v88, vcc
	v_cmp_le_i32_e32 vcc, v75, v219
	v_cmp_gt_i32_e64 s[6:7], v75, v220
	s_and_b64 vcc, vcc, s[6:7]
	v_add_u32_e32 v75, 48, v74
	v_cndmask_b32_e32 v89, v202, v89, vcc
	v_cmp_le_i32_e32 vcc, v75, v219
	v_cmp_gt_i32_e64 s[6:7], v75, v220
	s_and_b64 vcc, vcc, s[6:7]
	v_add_u32_e32 v75, 49, v74
	v_cndmask_b32_e32 v94, v202, v94, vcc
	v_cmp_le_i32_e32 vcc, v75, v219
	v_cmp_gt_i32_e64 s[6:7], v75, v220
	s_and_b64 vcc, vcc, s[6:7]
	v_add_u32_e32 v75, 50, v74
	v_cndmask_b32_e32 v95, v202, v95, vcc
	v_cmp_le_i32_e32 vcc, v75, v219
	v_cmp_gt_i32_e64 s[6:7], v75, v220
	s_and_b64 vcc, vcc, s[6:7]
	v_add_u32_e32 v74, 51, v74
	v_cndmask_b32_e32 v96, v202, v96, vcc
	v_cmp_le_i32_e32 vcc, v74, v219
	v_cmp_gt_i32_e64 s[6:7], v74, v220
	s_and_b64 vcc, vcc, s[6:7]
	v_cndmask_b32_e32 v97, v202, v97, vcc
; __device__ __forceinline__ void af_online_fast(f32x4 (&s)[4], bool colsel, float& m, float& l, f32x4 (&o)[8], half8 (&pf)[2], float SC) {
;     float lm = fmaxf(fmaxf(s[0][0], s[0][1]), fmaxf(s[0][2], s[0][3]));
; #pragma unroll
;     for (int kt = 1; kt < 4; ++kt) lm = fmaxf(lm, fmaxf(fmaxf(s[kt][0], s[kt][1]), fmaxf(s[kt][2], s[kt][3])));
;     if (__ballot(colsel && (lm * SC > m + 8.f)) != 0ull) {
;         float v = lm; v = fmaxf(v, __shfl_xor(v, 16)); v = fmaxf(v, __shfl_xor(v, 32));
;         const float mloc = colsel ? v * SC : -1.0e30f;
;         const float mn = fmaxf(m, mloc); const float al = __builtin_amdgcn_exp2f(m - mn); m = mn;
;         l *= al;
; #pragma unroll
;         for (int dt = 0; dt < 8; ++dt) o[dt] *= al;
;     }
.Lu2_606:
	v_max_f32_e32 v74, v63, v63
	v_max_f32_e32 v75, v62, v62
	v_max_f32_e32 v74, v75, v74
	v_max_f32_e32 v75, v65, v65
	v_max_f32_e32 v76, v64, v64
	v_max_f32_e32 v75, v76, v75
	v_max_f32_e32 v76, v85, v85
	v_max_f32_e32 v77, v84, v84
	v_max_f32_e32 v76, v77, v76
	v_max3_f32 v76, v82, v83, v76
	v_max3_f32 v74, v74, v75, v76
	v_max_f32_e32 v75, v89, v89
	v_max_f32_e32 v76, v88, v88
	v_max_f32_e32 v75, v76, v75
	v_max_f32_e32 v76, v97, v97
	v_max_f32_e32 v77, v96, v96
	v_max_f32_e32 v76, v77, v76
	v_max3_f32 v75, v86, v87, v75
	v_max3_f32 v76, v94, v95, v76
	v_max3_f32 v59, v74, v75, v76
	v_mul_f32_e32 v74, 0x3e0293ee, v59
	v_add_f32_e32 v75, 0x41000000, v217
	v_cmp_lt_i32_e64 s[6:7], -1, v219
	v_cmp_gt_f32_e32 vcc, v74, v75
	v_mov_b64_e32 v[76:77], v[164:165]
	v_mov_b64_e32 v[68:69], v[160:161]
	v_mov_b64_e32 v[52:53], v[156:157]
	v_mov_b64_e32 v[48:49], v[152:153]
	v_mov_b64_e32 v[72:73], v[148:149]
	v_mov_b64_e32 v[80:81], v[144:145]
	v_mov_b64_e32 v[92:93], v[140:141]
	v_mov_b64_e32 v[100:101], v[136:137]
	s_and_b64 vcc, s[6:7], vcc
	v_mov_b64_e32 v[74:75], v[162:163]
	v_mov_b64_e32 v[66:67], v[158:159]
	v_mov_b64_e32 v[50:51], v[154:155]
	v_mov_b64_e32 v[46:47], v[150:151]
	v_mov_b64_e32 v[70:71], v[146:147]
	v_mov_b64_e32 v[78:79], v[142:143]
	v_mov_b64_e32 v[90:91], v[138:139]
	v_mov_b64_e32 v[98:99], v[134:135]
	v_mov_b32_e32 v58, v216
	v_mov_b32_e32 v221, v217
	s_cbranch_vccz .Lu2_608
	ds_bpermute_b32 v74, v167, v59
	v_max_f32_e32 v75, v59, v59
	v_max_f32_e32 v76, v217, v217
	s_waitcnt lgkmcnt(0)
	v_max_f32_e32 v74, v74, v74
	v_max_f32_e32 v74, v75, v74
	ds_bpermute_b32 v75, v207, v74
	s_waitcnt lgkmcnt(0)
	v_max_f32_e32 v75, v75, v75
	v_max_f32_e32 v74, v74, v75
	v_mul_f32_e32 v74, 0x3e0293ee, v74
	v_cndmask_b32_e64 v74, v206, v74, s[6:7]
	v_max_f32_e32 v221, v76, v74
	v_sub_f32_e32 v74, v217, v221
	v_exp_f32_e32 v74, v74
	s_nop 0
	v_mul_f32_e32 v58, v216, v74
	v_pk_mul_f32 v[100:101], v[136:137], v[74:75] op_sel_hi:[1,0]
	v_pk_mul_f32 v[98:99], v[134:135], v[74:75] op_sel_hi:[1,0]
	v_pk_mul_f32 v[92:93], v[140:141], v[74:75] op_sel_hi:[1,0]
	v_pk_mul_f32 v[90:91], v[138:139], v[74:75] op_sel_hi:[1,0]
	v_pk_mul_f32 v[80:81], v[144:145], v[74:75] op_sel_hi:[1,0]
	v_pk_mul_f32 v[78:79], v[142:143], v[74:75] op_sel_hi:[1,0]
	v_pk_mul_f32 v[72:73], v[148:149], v[74:75] op_sel_hi:[1,0]
	v_pk_mul_f32 v[70:71], v[146:147], v[74:75] op_sel_hi:[1,0]
	v_pk_mul_f32 v[48:49], v[152:153], v[74:75] op_sel_hi:[1,0]
	v_pk_mul_f32 v[46:47], v[150:151], v[74:75] op_sel_hi:[1,0]
	v_pk_mul_f32 v[52:53], v[156:157], v[74:75] op_sel_hi:[1,0]
	v_pk_mul_f32 v[50:51], v[154:155], v[74:75] op_sel_hi:[1,0]
	v_pk_mul_f32 v[68:69], v[160:161], v[74:75] op_sel_hi:[1,0]
	v_pk_mul_f32 v[66:67], v[158:159], v[74:75] op_sel_hi:[1,0]
	v_pk_mul_f32 v[76:77], v[164:165], v[74:75] op_sel_hi:[1,0]
	v_pk_mul_f32 v[74:75], v[162:163], v[74:75] op_sel_hi:[1,0]
; #define LAS __attribute__((address_space(3)))
; #define AF_VWAIT(buf_, n_) asm volatile("s_waitcnt lgkmcnt(" #n_ ")" : "+v"(vr[buf_][0]), "+v"(vr[buf_][1]), "+v"(vr[buf_][2]), "+v"(vr[buf_][3]), "+v"(vr[buf_][4]), "+v"(vr[buf_][5]), "+v"(vr[buf_][6]), "+v"(vr[buf_][7]) :: "memory")
; template <bool a0, bool a1> __device__ __forceinline__ void af_pv(const LAS unsigned char* vbuf, unsigned vl0, int z, const half8 (&pf)[2][2], f32x4 (&o)[2][8]) {
;     const unsigned rb = (unsigned)(__UINTPTR_TYPE__)(vbuf + vl0);
;     s16x4 vr[2][8];
;     ...
;     AF_VLOAD(0, 0); AF_VLOAD(1, 2);
;     AF_VWAIT(0, 8); AF_VMMA(0, 0); AF_VLOAD(0, 4);
;     AF_VWAIT(1, 8); AF_VMMA(1, 2); AF_VLOAD(1, 6);
;     AF_VWAIT(0, 8); AF_VMMA(0, 4);
;     AF_VWAIT(1, 0); AF_VMMA(1, 6);
; __device__ __forceinline__ void af_online_fast(f32x4 (&s)[4], bool colsel, float& m, float& l, f32x4 (&o)[8], half8 (&pf)[2], float SC) {
;     ...
;     const float bias = colsel ? -m : -1.0e30f; float ps = 0.f;
; #pragma unroll
;     for (int kt = 0; kt < 4; ++kt)
; #pragma unroll
;         for (int jj = 0; jj < 4; ++jj) { const float p = __builtin_amdgcn_exp2f(__builtin_fmaf(s[kt][jj], SC, bias)); s[kt][jj] = p; ps += p; }
;     l += ps;
;     af_pack(s, pf);
; }
.Lu2_608:
	v_cndmask_b32_e64 v59, v206, -v221, s[6:7]
	v_fmamk_f32 v62, v62, 0x3e0293ee, v59
	v_exp_f32_e32 v222, v62
	v_fmamk_f32 v63, v63, 0x3e0293ee, v59
	v_exp_f32_e32 v224, v63
	v_fmamk_f32 v63, v64, 0x3e0293ee, v59
	v_exp_f32_e32 v225, v63
	v_fmamk_f32 v63, v65, 0x3e0293ee, v59
	v_exp_f32_e32 v228, v63
	v_fmamk_f32 v82, v82, 0x3e0293ee, v59
	v_add_f32_e32 v62, 0, v222
	v_exp_f32_e32 v226, v82
	v_fmamk_f32 v83, v83, 0x3e0293ee, v59
	v_add_f32_e32 v62, v224, v62
	v_exp_f32_e32 v229, v83
	v_fmamk_f32 v83, v84, 0x3e0293ee, v59
	v_add_f32_e32 v62, v225, v62
	v_exp_f32_e32 v227, v83
	v_fmamk_f32 v83, v85, 0x3e0293ee, v59
	v_add_f32_e32 v62, v228, v62
	v_exp_f32_e32 v230, v83
	v_fmamk_f32 v86, v86, 0x3e0293ee, v59
	v_add_f32_e32 v82, v226, v62
	v_exp_f32_e32 v232, v86
	v_fmamk_f32 v87, v87, 0x3e0293ee, v59
	v_add_f32_e32 v82, v229, v82
	v_exp_f32_e32 v233, v87
	v_fmamk_f32 v87, v88, 0x3e0293ee, v59
	v_add_f32_e32 v82, v227, v82
	v_exp_f32_e32 v234, v87
	v_fmamk_f32 v87, v89, 0x3e0293ee, v59
	v_add_f32_e32 v82, v230, v82
	v_exp_f32_e32 v235, v87
	v_fmamk_f32 v94, v94, 0x3e0293ee, v59
	v_add_f32_e32 v86, v232, v82
	v_exp_f32_e32 v236, v94
	v_fmamk_f32 v95, v95, 0x3e0293ee, v59
	v_add_f32_e32 v86, v233, v86
	v_exp_f32_e32 v237, v95
	v_fmamk_f32 v95, v96, 0x3e0293ee, v59
	v_add_f32_e32 v86, v234, v86
	v_exp_f32_e32 v231, v95
	v_fmac_f32_e32 v59, 0x3e0293ee, v97
	v_add_f32_e32 v86, v235, v86
	v_exp_f32_e32 v238, v59
	v_add_f32_e32 v94, v236, v86
	v_add_f32_e32 v94, v237, v94
	v_add_f32_e32 v94, v231, v94
	v_add_f32_e32 v94, v238, v94
	v_add_f32_e32 v223, v58, v94
	v_add_u32_e32 v94, s64, v174
	v_add_u32_e32 v239, 0x4000, v94
	v_add_u32_e32 v58, v177, v239
	v_add_u32_e32 v59, v178, v239
	ds_read_b64_tr_b16 v[62:63], v58
	ds_read_b64_tr_b16 v[64:65], v58 offset:4096
	ds_read_b64_tr_b16 v[82:83], v58 offset:8192
	ds_read_b64_tr_b16 v[84:85], v58 offset:12288
	ds_read_b64_tr_b16 v[86:87], v59
	ds_read_b64_tr_b16 v[88:89], v59 offset:4096
	ds_read_b64_tr_b16 v[94:95], v59 offset:8192
	ds_read_b64_tr_b16 v[96:97], v59 offset:12288
	v_add_u32_e32 v240, v179, v239
	v_add_u32_e32 v241, v180, v239
	ds_read_b64_tr_b16 v[38:39], v240
	ds_read_b64_tr_b16 v[40:41], v240 offset:4096
	ds_read_b64_tr_b16 v[42:43], v240 offset:8192
	ds_read_b64_tr_b16 v[44:45], v240 offset:12288
	ds_read_b64_tr_b16 v[54:55], v241
	ds_read_b64_tr_b16 v[56:57], v241 offset:4096
	ds_read_b64_tr_b16 v[58:59], v241 offset:8192
	ds_read_b64_tr_b16 v[60:61], v241 offset:12288
	s_waitcnt lgkmcnt(8)
	v_cvt_pk_f16_f32 v227, v227, v230
	v_cvt_pk_f16_f32 v226, v226, v229
	v_cvt_pk_f16_f32 v225, v225, v228
	v_cvt_pk_f16_f32 v224, v222, v224
	v_cvt_pk_f16_f32 v231, v231, v238
	v_cvt_pk_f16_f32 v230, v236, v237
	v_mfma_f32_16x16x32_f16 v[62:65], v[62:65], v[224:227], v[98:101]
	v_cvt_pk_f16_f32 v229, v234, v235
	v_cvt_pk_f16_f32 v228, v232, v233
	v_mfma_f32_16x16x32_f16 v[86:89], v[86:89], v[224:227], v[90:93]
	s_nop 0
	v_mfma_f32_16x16x32_f16 v[98:101], v[82:85], v[228:231], v[62:65]
	v_mfma_f32_16x16x32_f16 v[90:93], v[94:97], v[228:231], v[86:89]
	v_add_u32_e32 v222, v181, v239
	v_add_u32_e32 v232, v182, v239
	ds_read_b64_tr_b16 v[62:63], v222
	ds_read_b64_tr_b16 v[64:65], v222 offset:4096
	ds_read_b64_tr_b16 v[82:83], v222 offset:8192
	ds_read_b64_tr_b16 v[84:85], v222 offset:12288
	ds_read_b64_tr_b16 v[86:87], v232
	ds_read_b64_tr_b16 v[88:89], v232 offset:4096
	ds_read_b64_tr_b16 v[94:95], v232 offset:8192
	ds_read_b64_tr_b16 v[96:97], v232 offset:12288
	s_waitcnt lgkmcnt(8)
	s_nop 0
	v_mfma_f32_16x16x32_f16 v[78:81], v[38:41], v[224:227], v[78:81]
	v_mfma_f32_16x16x32_f16 v[70:73], v[54:57], v[224:227], v[70:73]
	v_mfma_f32_16x16x32_f16 v[78:81], v[42:45], v[228:231], v[78:81]
	v_mfma_f32_16x16x32_f16 v[70:73], v[58:61], v[228:231], v[70:73]
	v_add_u32_e32 v58, v183, v239
	v_add_u32_e32 v59, v184, v239
	ds_read_b64_tr_b16 v[236:237], v58
	ds_read_b64_tr_b16 v[238:239], v58 offset:4096
	ds_read_b64_tr_b16 v[42:43], v58 offset:8192
	ds_read_b64_tr_b16 v[44:45], v58 offset:12288
	ds_read_b64_tr_b16 v[232:233], v59
	ds_read_b64_tr_b16 v[234:235], v59 offset:4096
	ds_read_b64_tr_b16 v[38:39], v59 offset:8192
	ds_read_b64_tr_b16 v[40:41], v59 offset:12288
	s_waitcnt lgkmcnt(8)
	s_nop 0
	v_mfma_f32_16x16x32_f16 v[62:65], v[62:65], v[224:227], v[46:49]
	v_mfma_f32_16x16x32_f16 v[86:89], v[86:89], v[224:227], v[50:53]
	v_mfma_f32_16x16x32_f16 v[58:61], v[82:85], v[228:231], v[62:65]
	v_mfma_f32_16x16x32_f16 v[54:57], v[94:97], v[228:231], v[86:89]
	s_waitcnt lgkmcnt(0)
	s_nop 0
	v_mfma_f32_16x16x32_f16 v[94:97], v[236:239], v[224:227], v[66:69]
	v_mfma_f32_16x16x32_f16 v[42:45], v[42:45], v[228:231], v[94:97]
	v_mfma_f32_16x16x32_f16 v[94:97], v[232:235], v[224:227], v[74:77]
	v_mfma_f32_16x16x32_f16 v[38:41], v[38:41], v[228:231], v[94:97]
	v_mov_b64_e32 v[48:49], v[132:133]
	v_mov_b64_e32 v[52:53], v[128:129]
	v_mov_b64_e32 v[64:65], v[124:125]
	v_mov_b64_e32 v[68:69], v[120:121]
	v_mov_b64_e32 v[76:77], v[116:117]
	v_mov_b64_e32 v[84:85], v[112:113]
	v_mov_b64_e32 v[88:89], v[108:109]
	v_mov_b64_e32 v[96:97], v[104:105]
	v_mov_b32_e32 v224, v4
	v_mov_b32_e32 v222, v5
	v_mov_b64_e32 v[46:47], v[130:131]
	v_mov_b64_e32 v[50:51], v[126:127]
	v_mov_b64_e32 v[62:63], v[122:123]
	v_mov_b64_e32 v[66:67], v[118:119]
	v_mov_b64_e32 v[74:75], v[114:115]
	v_mov_b64_e32 v[82:83], v[110:111]
	v_mov_b64_e32 v[86:87], v[106:107]
	v_mov_b64_e32 v[94:95], v[102:103]

; #define LAS __attribute__((address_space(3)))
; template <bool a0, bool a1> __device__ __forceinline__ void af_qk(const LAS unsigned char* kbuf, const unsigned (&kl)[4], const half8 (&qf)[2][4], f32x4 (&s)[2][4]) {
;     const LAS unsigned char* ka[4];
;     { int _ln; asm volatile("v_mov_b32 %0, %1" : "=v"(_ln) : "v"(kl[0]));
;       const int fr_ = _ln & 15, e_ = (_ln >> 4) ^ fr_;
; #pragma unroll
;       for (int ks = 0; ks < 4; ++ks) ka[ks] = kbuf + fr_ * 256 + ((e_ ^ (4 * ks)) << 4); }
;     half8 kf[2][4];
; #pragma unroll
;     for (int ks = 0; ks < 4; ++ks) kf[0][ks] = *(const LAS half8*)(ka[ks]);
; #pragma unroll
;     for (int kt = 0; kt < 4; ++kt) {
;         if (kt < 3) {
; #pragma unroll
;             for (int ks = 0; ks < 4; ++ks) kf[(kt + 1) & 1][ks] = *(const LAS half8*)(ka[ks] + (kt + 1) * 4096); }
;         s[0][kt] = (f32x4){0.f, 0.f, 0.f, 0.f}; s[1][kt] = (f32x4){0.f, 0.f, 0.f, 0.f};
; #pragma unroll
;         for (int ks = 0; ks < 4; ++ks) {
;             if (a0) s[0][kt] = __builtin_amdgcn_mfma_f32_16x16x32_f16(kf[kt & 1][ks], qf[0][ks], s[0][kt], 0, 0, 0);
;             if (a1) s[1][kt] = __builtin_amdgcn_mfma_f32_16x16x32_f16(kf[kt & 1][ks], qf[1][ks], s[1][kt], 0, 0, 0); }
;         __builtin_amdgcn_sched_barrier(0);
;     }
; __device__ __forceinline__ void af_maskraw(f32x4 (&s)[4], int mbase, int mstep, int fq, int hi, int lo) {
; #pragma unroll
;     for (int kt = 0; kt < 4; ++kt)
; #pragma unroll
;         for (int jj = 0; jj < 4; ++jj) { const int met = mbase + mstep * (16 * kt + 4 * fq + jj); s[kt][jj] = (met <= hi && met > lo) ? s[kt][jj] : -3.0e38f; }
; }
.Lu2_610:
	s_andn2_b64 vcc, exec, s[6:7]
	s_cbranch_vccnz .Lu2_619
	v_mov_b32 v94, v172
	s_nop 0
	v_and_b32_e32 v95, 15, v94
	v_lshl_add_u32 v50, v95, 8, s64
	v_lshlrev_b32_e32 v95, 4, v95
	v_bitop3_b32 v51, v95, v94, -16 bitop3:0x78
	v_add_u32_e32 v78, v50, v51
	ds_read_b128 v[94:97], v78
	ds_read_b128 v[86:89], v78 offset:4096
	v_xad_u32 v79, v51, 64, v50
	s_waitcnt lgkmcnt(0)
	v_mfma_f32_16x16x32_f16 v[82:85], v[94:97], v[6:9], 0
	ds_read_b128 v[74:77], v79
	ds_read_b128 v[66:69], v79 offset:4096
	v_xad_u32 v80, v51, s77, v50
	v_xad_u32 v70, v51, s78, v50
	v_mfma_f32_16x16x32_f16 v[94:97], v[94:97], v[22:25], 0
	s_waitcnt lgkmcnt(0)
	v_mfma_f32_16x16x32_f16 v[82:85], v[74:77], v[10:13], v[82:85]
	v_mfma_f32_16x16x32_f16 v[94:97], v[74:77], v[26:29], v[94:97]
	ds_read_b128 v[74:77], v80
	ds_read_b128 v[62:65], v80 offset:4096
	s_waitcnt lgkmcnt(0)
	v_mfma_f32_16x16x32_f16 v[82:85], v[74:77], v[14:17], v[82:85]
	v_mfma_f32_16x16x32_f16 v[94:97], v[74:77], v[30:33], v[94:97]
	ds_read_b128 v[74:77], v70
	ds_read_b128 v[98:101], v70 offset:4096
	s_waitcnt lgkmcnt(0)
	v_mfma_f32_16x16x32_f16 v[46:49], v[74:77], v[18:21], v[82:85]
	v_mfma_f32_16x16x32_f16 v[74:77], v[74:77], v[34:37], v[94:97]
	v_mfma_f32_16x16x32_f16 v[94:97], v[86:89], v[6:9], 0
	v_mfma_f32_16x16x32_f16 v[86:89], v[86:89], v[22:25], 0
	v_mfma_f32_16x16x32_f16 v[94:97], v[66:69], v[10:13], v[94:97]
	v_mfma_f32_16x16x32_f16 v[86:89], v[66:69], v[26:29], v[86:89]
	v_mfma_f32_16x16x32_f16 v[94:97], v[62:65], v[14:17], v[94:97]
	v_mfma_f32_16x16x32_f16 v[86:89], v[62:65], v[30:33], v[86:89]
	v_mfma_f32_16x16x32_f16 v[50:53], v[98:101], v[18:21], v[94:97]
	s_nop 5
	ds_read_b128 v[94:97], v78 offset:8192
	ds_read_b128 v[66:69], v79 offset:8192
	ds_read_b128 v[62:65], v80 offset:8192
	ds_read_b128 v[90:93], v70 offset:8192
	v_mfma_f32_16x16x32_f16 v[82:85], v[98:101], v[34:37], v[86:89]
	s_waitcnt lgkmcnt(0)
	v_mfma_f32_16x16x32_f16 v[86:89], v[94:97], v[6:9], 0
	v_mfma_f32_16x16x32_f16 v[94:97], v[94:97], v[22:25], 0
	v_mfma_f32_16x16x32_f16 v[86:89], v[66:69], v[10:13], v[86:89]
	v_mfma_f32_16x16x32_f16 v[94:97], v[66:69], v[26:29], v[94:97]
	ds_read_b128 v[66:69], v78 offset:12288
	ds_read_b128 v[98:101], v79 offset:12288
	ds_read_b128 v[78:81], v80 offset:12288
	ds_read_b128 v[70:73], v70 offset:12288
	v_mfma_f32_16x16x32_f16 v[86:89], v[62:65], v[14:17], v[86:89]
	v_mfma_f32_16x16x32_f16 v[94:97], v[62:65], v[30:33], v[94:97]
	v_mfma_f32_16x16x32_f16 v[62:65], v[90:93], v[18:21], v[86:89]
	v_mfma_f32_16x16x32_f16 v[86:89], v[90:93], v[34:37], v[94:97]
	s_waitcnt lgkmcnt(0)
	v_mfma_f32_16x16x32_f16 v[94:97], v[66:69], v[6:9], 0
	v_mfma_f32_16x16x32_f16 v[66:69], v[66:69], v[22:25], 0
	v_mfma_f32_16x16x32_f16 v[94:97], v[98:101], v[10:13], v[94:97]
	v_mfma_f32_16x16x32_f16 v[66:69], v[98:101], v[26:29], v[66:69]
	v_mfma_f32_16x16x32_f16 v[94:97], v[78:81], v[14:17], v[94:97]
	v_mfma_f32_16x16x32_f16 v[98:101], v[78:81], v[30:33], v[66:69]
	v_mfma_f32_16x16x32_f16 v[66:69], v[70:73], v[18:21], v[94:97]
	v_mfma_f32_16x16x32_f16 v[94:97], v[70:73], v[34:37], v[98:101]
	s_nop 5
	v_cndmask_b32_e64 v98, 0, 1, s[60:61]
	v_add_u32_e32 v72, s16, v173
	v_cmp_ne_u32_e64 s[8:9], 1, v98
	s_andn2_b64 vcc, exec, s[60:61]
	v_add_u32_e32 v71, 2, v72
	v_add_u32_e32 v70, 3, v72
	v_add_u32_e32 v81, 16, v72
	v_add_u32_e32 v80, 17, v72
	v_add_u32_e32 v79, 18, v72
	v_add_u32_e32 v78, 19, v72
	v_add_u32_e32 v93, 32, v72
	v_add_u32_e32 v92, 33, v72
	v_add_u32_e32 v91, 34, v72
	v_add_u32_e32 v90, 35, v72
	v_add_u32_e32 v101, 48, v72
	v_add_u32_e32 v100, 49, v72
	v_add_u32_e32 v99, 50, v72
	v_add_u32_e32 v98, 51, v72
	s_cbranch_vccnz .Lu2_613
	v_cmp_le_i32_e32 vcc, v72, v219
	v_cmp_gt_i32_e64 s[6:7], v72, v220
	s_and_b64 vcc, vcc, s[6:7]
	v_cndmask_b32_e32 v46, v202, v46, vcc
	v_cmp_lt_i32_e32 vcc, v72, v219
	v_cmp_ge_i32_e64 s[6:7], v72, v220
	s_and_b64 vcc, vcc, s[6:7]
	v_cndmask_b32_e32 v47, v202, v47, vcc
	v_cmp_le_i32_e32 vcc, v71, v219
	v_cmp_gt_i32_e64 s[6:7], v71, v220
	s_and_b64 vcc, vcc, s[6:7]
	v_cndmask_b32_e32 v48, v202, v48, vcc
	v_cmp_le_i32_e32 vcc, v70, v219
	v_cmp_gt_i32_e64 s[6:7], v70, v220
	s_and_b64 vcc, vcc, s[6:7]
	v_cndmask_b32_e32 v49, v202, v49, vcc
	v_cmp_le_i32_e32 vcc, v81, v219
	v_cmp_gt_i32_e64 s[6:7], v81, v220
	s_and_b64 vcc, vcc, s[6:7]
	v_cndmask_b32_e32 v50, v202, v50, vcc
	v_cmp_le_i32_e32 vcc, v80, v219
	v_cmp_gt_i32_e64 s[6:7], v80, v220
	s_and_b64 vcc, vcc, s[6:7]
	v_cndmask_b32_e32 v51, v202, v51, vcc
	v_cmp_le_i32_e32 vcc, v79, v219
	v_cmp_gt_i32_e64 s[6:7], v79, v220
	s_and_b64 vcc, vcc, s[6:7]
	v_cndmask_b32_e32 v52, v202, v52, vcc
	v_cmp_le_i32_e32 vcc, v78, v219
	v_cmp_gt_i32_e64 s[6:7], v78, v220
	s_and_b64 vcc, vcc, s[6:7]
	v_cndmask_b32_e32 v53, v202, v53, vcc
	v_cmp_le_i32_e32 vcc, v93, v219
	v_cmp_gt_i32_e64 s[6:7], v93, v220
	s_and_b64 vcc, vcc, s[6:7]
	v_cndmask_b32_e32 v62, v202, v62, vcc
	v_cmp_le_i32_e32 vcc, v92, v219
	v_cmp_gt_i32_e64 s[6:7], v92, v220
	s_and_b64 vcc, vcc, s[6:7]
	v_cndmask_b32_e32 v63, v202, v63, vcc
	v_cmp_le_i32_e32 vcc, v91, v219
	v_cmp_gt_i32_e64 s[6:7], v91, v220
	s_and_b64 vcc, vcc, s[6:7]
	v_cndmask_b32_e32 v64, v202, v64, vcc
	v_cmp_le_i32_e32 vcc, v90, v219
	v_cmp_gt_i32_e64 s[6:7], v90, v220
	s_and_b64 vcc, vcc, s[6:7]
	v_cndmask_b32_e32 v65, v202, v65, vcc
	v_cmp_le_i32_e32 vcc, v101, v219
	v_cmp_gt_i32_e64 s[6:7], v101, v220
	s_and_b64 vcc, vcc, s[6:7]
	v_cndmask_b32_e32 v66, v202, v66, vcc
	v_cmp_le_i32_e32 vcc, v100, v219
	v_cmp_gt_i32_e64 s[6:7], v100, v220
	s_and_b64 vcc, vcc, s[6:7]
	v_cndmask_b32_e32 v67, v202, v67, vcc
	v_cmp_le_i32_e32 vcc, v99, v219
	v_cmp_gt_i32_e64 s[6:7], v99, v220
	s_and_b64 vcc, vcc, s[6:7]
	v_cndmask_b32_e32 v68, v202, v68, vcc
	v_cmp_le_i32_e32 vcc, v98, v219
	v_cmp_gt_i32_e64 s[6:7], v98, v220
	s_and_b64 vcc, vcc, s[6:7]
	v_cndmask_b32_e32 v69, v202, v69, vcc
; __device__ __forceinline__ void af_maskraw(f32x4 (&s)[4], int mbase, int mstep, int fq, int hi, int lo) {
; #pragma unroll
;     for (int kt = 0; kt < 4; ++kt)
; #pragma unroll
;         for (int jj = 0; jj < 4; ++jj) { const int met = mbase + mstep * (16 * kt + 4 * fq + jj); s[kt][jj] = (met <= hi && met > lo) ? s[kt][jj] : -3.0e38f; }
; }
; __device__ __forceinline__ void af_online_fast(f32x4 (&s)[4], bool colsel, float& m, float& l, f32x4 (&o)[8], half8 (&pf)[2], float SC) {
;     float lm = fmaxf(fmaxf(s[0][0], s[0][1]), fmaxf(s[0][2], s[0][3]));
; #pragma unroll
;     for (int kt = 1; kt < 4; ++kt) lm = fmaxf(lm, fmaxf(fmaxf(s[kt][0], s[kt][1]), fmaxf(s[kt][2], s[kt][3])));
;     if (__ballot(colsel && (lm * SC > m + 8.f)) != 0ull) {
;         float v = lm; v = fmaxf(v, __shfl_xor(v, 16)); v = fmaxf(v, __shfl_xor(v, 32));
;         const float mloc = colsel ? v * SC : -1.0e30f;
;         const float mn = fmaxf(m, mloc); const float al = __builtin_amdgcn_exp2f(m - mn); m = mn;
;         l *= al;
; #pragma unroll
;         for (int dt = 0; dt < 8; ++dt) o[dt] *= al;
;     }
.Lu2_613:
	v_max_f32_e32 v73, v47, v47
	v_max_f32_e32 v58, v46, v46
	v_max_f32_e32 v73, v58, v73
	v_max_f32_e32 v58, v49, v49
	v_max_f32_e32 v59, v48, v48
	v_max_f32_e32 v58, v59, v58
	v_max_f32_e32 v59, v53, v53
	v_max_f32_e32 v60, v52, v52
	v_max_f32_e32 v59, v60, v59
	v_max3_f32 v59, v50, v51, v59
	v_max3_f32 v73, v73, v58, v59
	v_max_f32_e32 v58, v65, v65
	v_max_f32_e32 v59, v64, v64
	v_max_f32_e32 v58, v59, v58
	v_max_f32_e32 v59, v69, v69
	v_max_f32_e32 v60, v68, v68
	v_max_f32_e32 v59, v60, v59
	v_max3_f32 v58, v62, v63, v58
	v_max3_f32 v59, v66, v67, v59
	v_max3_f32 v73, v73, v58, v59
	v_mul_f32_e32 v58, 0x3e0293ee, v73
	v_add_f32_e32 v59, 0x41000000, v217
	v_cmp_lt_i32_e64 s[6:7], -1, v219
	v_cmp_gt_f32_e32 vcc, v58, v59
	s_and_b64 vcc, s[6:7], vcc
	s_cbranch_vccz .Lu2_621
	ds_bpermute_b32 v58, v167, v73
	v_max_f32_e32 v73, v73, v73
	s_waitcnt lgkmcnt(0)
	v_max_f32_e32 v58, v58, v58
	v_max_f32_e32 v73, v73, v58
	ds_bpermute_b32 v58, v207, v73
	s_waitcnt lgkmcnt(0)
	v_max_f32_e32 v58, v58, v58
	v_max_f32_e32 v73, v73, v58
	v_mul_f32_e32 v73, 0x3e0293ee, v73
	v_cndmask_b32_e64 v73, v206, v73, s[6:7]
	v_max_f32_e32 v58, v217, v217
	v_max_f32_e32 v221, v58, v73
	v_sub_f32_e32 v73, v217, v221
	v_exp_f32_e32 v58, v73
	s_nop 0
	v_mul_f32_e32 v216, v216, v58
	v_pk_mul_f32 v[136:137], v[136:137], v[58:59] op_sel_hi:[1,0]
	v_pk_mul_f32 v[134:135], v[134:135], v[58:59] op_sel_hi:[1,0]
	v_pk_mul_f32 v[140:141], v[140:141], v[58:59] op_sel_hi:[1,0]
	v_pk_mul_f32 v[138:139], v[138:139], v[58:59] op_sel_hi:[1,0]
	v_pk_mul_f32 v[144:145], v[144:145], v[58:59] op_sel_hi:[1,0]
	v_pk_mul_f32 v[142:143], v[142:143], v[58:59] op_sel_hi:[1,0]
	v_pk_mul_f32 v[148:149], v[148:149], v[58:59] op_sel_hi:[1,0]
	v_pk_mul_f32 v[146:147], v[146:147], v[58:59] op_sel_hi:[1,0]
	v_pk_mul_f32 v[152:153], v[152:153], v[58:59] op_sel_hi:[1,0]
	v_pk_mul_f32 v[150:151], v[150:151], v[58:59] op_sel_hi:[1,0]
	v_pk_mul_f32 v[156:157], v[156:157], v[58:59] op_sel_hi:[1,0]
	v_pk_mul_f32 v[154:155], v[154:155], v[58:59] op_sel_hi:[1,0]
	v_pk_mul_f32 v[160:161], v[160:161], v[58:59] op_sel_hi:[1,0]
	v_pk_mul_f32 v[158:159], v[158:159], v[58:59] op_sel_hi:[1,0]
	v_pk_mul_f32 v[164:165], v[164:165], v[58:59] op_sel_hi:[1,0]
	v_pk_mul_f32 v[162:163], v[162:163], v[58:59] op_sel_hi:[1,0]
	s_and_b64 vcc, exec, s[8:9]
	s_cbranch_vccnz .Lu2_616
.Lu2_615:
	v_cmp_le_i32_e32 vcc, v72, v2
	v_cmp_gt_i32_e64 s[8:9], v72, v218
	s_and_b64 vcc, vcc, s[8:9]
	v_cndmask_b32_e32 v74, v202, v74, vcc
	v_cmp_lt_i32_e32 vcc, v72, v2
	v_cmp_ge_i32_e64 s[8:9], v72, v218
	s_and_b64 vcc, vcc, s[8:9]
	v_cndmask_b32_e32 v75, v202, v75, vcc
	v_cmp_le_i32_e32 vcc, v71, v2
	v_cmp_gt_i32_e64 s[8:9], v71, v218
	s_and_b64 vcc, vcc, s[8:9]
	v_cndmask_b32_e32 v76, v202, v76, vcc
	v_cmp_le_i32_e32 vcc, v70, v2
	v_cmp_gt_i32_e64 s[8:9], v70, v218
	s_and_b64 vcc, vcc, s[8:9]
	v_cndmask_b32_e32 v77, v202, v77, vcc
	v_cmp_le_i32_e32 vcc, v81, v2
	v_cmp_gt_i32_e64 s[8:9], v81, v218
	s_and_b64 vcc, vcc, s[8:9]
	v_cndmask_b32_e32 v82, v202, v82, vcc
	v_cmp_le_i32_e32 vcc, v80, v2
	v_cmp_gt_i32_e64 s[8:9], v80, v218
	s_and_b64 vcc, vcc, s[8:9]
	v_cndmask_b32_e32 v83, v202, v83, vcc
	v_cmp_le_i32_e32 vcc, v79, v2
	v_cmp_gt_i32_e64 s[8:9], v79, v218
	s_and_b64 vcc, vcc, s[8:9]
	v_cndmask_b32_e32 v84, v202, v84, vcc
	v_cmp_le_i32_e32 vcc, v78, v2
	v_cmp_gt_i32_e64 s[8:9], v78, v218
	s_and_b64 vcc, vcc, s[8:9]
	v_cndmask_b32_e32 v85, v202, v85, vcc
	v_cmp_le_i32_e32 vcc, v93, v2
	v_cmp_gt_i32_e64 s[8:9], v93, v218
	s_and_b64 vcc, vcc, s[8:9]
	v_cndmask_b32_e32 v86, v202, v86, vcc
	v_cmp_le_i32_e32 vcc, v92, v2
	v_cmp_gt_i32_e64 s[8:9], v92, v218
	s_and_b64 vcc, vcc, s[8:9]
	v_cndmask_b32_e32 v87, v202, v87, vcc
	v_cmp_le_i32_e32 vcc, v91, v2
	v_cmp_gt_i32_e64 s[8:9], v91, v218
	s_and_b64 vcc, vcc, s[8:9]
	v_cndmask_b32_e32 v88, v202, v88, vcc
	v_cmp_le_i32_e32 vcc, v90, v2
	v_cmp_gt_i32_e64 s[8:9], v90, v218
	s_and_b64 vcc, vcc, s[8:9]
	v_cndmask_b32_e32 v89, v202, v89, vcc
	v_cmp_le_i32_e32 vcc, v101, v2
	v_cmp_gt_i32_e64 s[8:9], v101, v218
	s_and_b64 vcc, vcc, s[8:9]
	v_cndmask_b32_e32 v94, v202, v94, vcc
	v_cmp_le_i32_e32 vcc, v100, v2
	v_cmp_gt_i32_e64 s[8:9], v100, v218
	s_and_b64 vcc, vcc, s[8:9]
	v_cndmask_b32_e32 v95, v202, v95, vcc
	v_cmp_le_i32_e32 vcc, v99, v2
	v_cmp_gt_i32_e64 s[8:9], v99, v218
	s_and_b64 vcc, vcc, s[8:9]
	v_cndmask_b32_e32 v96, v202, v96, vcc
	v_cmp_le_i32_e32 vcc, v98, v2
	v_cmp_gt_i32_e64 s[8:9], v98, v218
	s_and_b64 vcc, vcc, s[8:9]
	v_cndmask_b32_e32 v97, v202, v97, vcc
.Lu2_616:
	v_cmp_lt_i32_e64 s[8:9], -1, v2
	v_max_f32_e32 v2, v75, v75
	v_max_f32_e32 v98, v74, v74
	v_max_f32_e32 v2, v98, v2
	v_max_f32_e32 v98, v77, v77
	v_max_f32_e32 v99, v76, v76
	v_max_f32_e32 v98, v99, v98
	v_max_f32_e32 v99, v85, v85
	v_max_f32_e32 v100, v84, v84
	v_max_f32_e32 v99, v100, v99
	v_max3_f32 v99, v82, v83, v99
	v_max3_f32 v2, v2, v98, v99
	v_max_f32_e32 v98, v89, v89
	v_max_f32_e32 v99, v88, v88
	v_max_f32_e32 v98, v99, v98
	v_max_f32_e32 v99, v97, v97
	v_max_f32_e32 v100, v96, v96
	v_max_f32_e32 v99, v100, v99
	v_max3_f32 v98, v86, v87, v98
	v_max3_f32 v99, v94, v95, v99
	v_max3_f32 v2, v2, v98, v99
	v_mul_f32_e32 v98, 0x3e0293ee, v2
	v_add_f32_e32 v99, 0x41000000, v4
	v_cmp_gt_f32_e32 vcc, v98, v99
	s_and_b64 vcc, s[8:9], vcc
	s_cbranch_vccz .Lu2_618
	ds_bpermute_b32 v98, v167, v2
	v_max_f32_e32 v2, v2, v2
	s_waitcnt lgkmcnt(0)
	v_max_f32_e32 v98, v98, v98
	v_max_f32_e32 v2, v2, v98
	ds_bpermute_b32 v98, v207, v2
	s_waitcnt lgkmcnt(0)
	v_max_f32_e32 v98, v98, v98
	v_max_f32_e32 v2, v2, v98
	v_mul_f32_e32 v2, 0x3e0293ee, v2
	v_cndmask_b32_e64 v2, v206, v2, s[8:9]
	v_max_f32_e32 v98, v4, v4
	v_max_f32_e32 v98, v98, v2
	v_sub_f32_e32 v2, v4, v98
	v_exp_f32_e32 v2, v2
	v_mov_b32_e32 v4, v98
	v_mul_f32_e32 v5, v5, v2
	v_pk_mul_f32 v[104:105], v[104:105], v[2:3] op_sel_hi:[1,0]
	v_pk_mul_f32 v[102:103], v[102:103], v[2:3] op_sel_hi:[1,0]
	v_pk_mul_f32 v[108:109], v[108:109], v[2:3] op_sel_hi:[1,0]
	v_pk_mul_f32 v[106:107], v[106:107], v[2:3] op_sel_hi:[1,0]
	v_pk_mul_f32 v[112:113], v[112:113], v[2:3] op_sel_hi:[1,0]
	v_pk_mul_f32 v[110:111], v[110:111], v[2:3] op_sel_hi:[1,0]
	v_pk_mul_f32 v[116:117], v[116:117], v[2:3] op_sel_hi:[1,0]
	v_pk_mul_f32 v[114:115], v[114:115], v[2:3] op_sel_hi:[1,0]
	v_pk_mul_f32 v[120:121], v[120:121], v[2:3] op_sel_hi:[1,0]
	v_pk_mul_f32 v[118:119], v[118:119], v[2:3] op_sel_hi:[1,0]
	v_pk_mul_f32 v[124:125], v[124:125], v[2:3] op_sel_hi:[1,0]
	v_pk_mul_f32 v[122:123], v[122:123], v[2:3] op_sel_hi:[1,0]
	v_pk_mul_f32 v[128:129], v[128:129], v[2:3] op_sel_hi:[1,0]
	v_pk_mul_f32 v[126:127], v[126:127], v[2:3] op_sel_hi:[1,0]
	v_pk_mul_f32 v[132:133], v[132:133], v[2:3] op_sel_hi:[1,0]
	v_pk_mul_f32 v[130:131], v[130:131], v[2:3] op_sel_hi:[1,0]
; #define LAS __attribute__((address_space(3)))
; template <bool a0, bool a1> __device__ __forceinline__ void af_pv(const LAS unsigned char* vbuf, unsigned vl0, int z, const half8 (&pf)[2][2], f32x4 (&o)[2][8]) {
;     const unsigned rb = (unsigned)(__UINTPTR_TYPE__)(vbuf + vl0);
;     s16x4 vr[2][8];
; __device__ __forceinline__ void af_online_fast(f32x4 (&s)[4], bool colsel, float& m, float& l, f32x4 (&o)[8], half8 (&pf)[2], float SC) {
;     ...
;     const float bias = colsel ? -m : -1.0e30f; float ps = 0.f;
; #pragma unroll
;     for (int kt = 0; kt < 4; ++kt)
; #pragma unroll
;         for (int jj = 0; jj < 4; ++jj) { const float p = __builtin_amdgcn_exp2f(__builtin_fmaf(s[kt][jj], SC, bias)); s[kt][jj] = p; ps += p; }
;     l += ps;
;     af_pack(s, pf);
.Lu2_618:
	v_cndmask_b32_e64 v2, v206, -v221, s[6:7]
	v_fmamk_f32 v46, v46, 0x3e0293ee, v2
	v_exp_f32_e32 v98, v46
	v_fmamk_f32 v47, v47, 0x3e0293ee, v2
	v_exp_f32_e32 v99, v47
	v_fmamk_f32 v47, v48, 0x3e0293ee, v2
	v_exp_f32_e32 v100, v47
	v_fmamk_f32 v47, v49, 0x3e0293ee, v2
	v_exp_f32_e32 v101, v47
	v_fmamk_f32 v50, v50, 0x3e0293ee, v2
	v_add_f32_e32 v46, 0, v98
	v_exp_f32_e32 v90, v50
	v_fmamk_f32 v51, v51, 0x3e0293ee, v2
	v_add_f32_e32 v46, v99, v46
	v_exp_f32_e32 v91, v51
	v_fmamk_f32 v51, v52, 0x3e0293ee, v2
	v_add_f32_e32 v46, v100, v46
	v_exp_f32_e32 v92, v51
	v_fmamk_f32 v51, v53, 0x3e0293ee, v2
	v_add_f32_e32 v46, v101, v46
	v_exp_f32_e32 v93, v51
	v_fmamk_f32 v62, v62, 0x3e0293ee, v2
	v_add_f32_e32 v50, v90, v46
	v_exp_f32_e32 v78, v62
	v_fmamk_f32 v63, v63, 0x3e0293ee, v2
	v_add_f32_e32 v50, v91, v50
	v_exp_f32_e32 v79, v63
	v_fmamk_f32 v63, v64, 0x3e0293ee, v2
	v_add_f32_e32 v50, v92, v50
	v_exp_f32_e32 v80, v63
	v_fmamk_f32 v63, v65, 0x3e0293ee, v2
	v_add_f32_e32 v50, v93, v50
	v_exp_f32_e32 v81, v63
	v_fmamk_f32 v66, v66, 0x3e0293ee, v2
	v_add_f32_e32 v62, v78, v50
	v_exp_f32_e32 v70, v66
	v_fmamk_f32 v67, v67, 0x3e0293ee, v2
	v_add_f32_e32 v62, v79, v62
	v_exp_f32_e32 v71, v67
	v_fmamk_f32 v67, v68, 0x3e0293ee, v2
	v_add_f32_e32 v62, v80, v62
	v_exp_f32_e32 v72, v67
	v_fmac_f32_e32 v2, 0x3e0293ee, v69
	v_add_f32_e32 v62, v81, v62
	v_exp_f32_e32 v2, v2
	v_add_f32_e32 v66, v70, v62
	v_add_f32_e32 v66, v71, v66
	v_add_f32_e32 v66, v72, v66
	v_add_f32_e32 v66, v2, v66
	v_add_f32_e32 v223, v216, v66
	v_cndmask_b32_e64 v66, v206, -v4, s[8:9]
	v_fmamk_f32 v74, v74, 0x3e0293ee, v66
	v_exp_f32_e32 v73, v74
	v_fmamk_f32 v75, v75, 0x3e0293ee, v66
	v_exp_f32_e32 v58, v75
	v_fmamk_f32 v75, v76, 0x3e0293ee, v66
	v_exp_f32_e32 v59, v75
	v_fmamk_f32 v75, v77, 0x3e0293ee, v66
	v_exp_f32_e32 v60, v75
	v_fmamk_f32 v82, v82, 0x3e0293ee, v66
	v_add_f32_e32 v74, 0, v73
	v_exp_f32_e32 v61, v82
	v_fmamk_f32 v83, v83, 0x3e0293ee, v66
	v_add_f32_e32 v74, v58, v74
	v_exp_f32_e32 v54, v83
	v_fmamk_f32 v83, v84, 0x3e0293ee, v66
	v_add_f32_e32 v74, v59, v74
	v_exp_f32_e32 v55, v83
	v_fmamk_f32 v83, v85, 0x3e0293ee, v66
	v_add_f32_e32 v74, v60, v74
	v_exp_f32_e32 v56, v83
	v_fmamk_f32 v86, v86, 0x3e0293ee, v66
	v_add_f32_e32 v82, v61, v74
	v_exp_f32_e32 v57, v86
	v_fmamk_f32 v87, v87, 0x3e0293ee, v66
	v_add_f32_e32 v82, v54, v82
	v_exp_f32_e32 v42, v87
	v_fmamk_f32 v87, v88, 0x3e0293ee, v66
	v_add_f32_e32 v82, v55, v82
	v_exp_f32_e32 v43, v87
	v_fmamk_f32 v87, v89, 0x3e0293ee, v66
	v_add_f32_e32 v82, v56, v82
	v_exp_f32_e32 v44, v87
	v_fmamk_f32 v94, v94, 0x3e0293ee, v66
	v_add_f32_e32 v86, v57, v82
	v_exp_f32_e32 v45, v94
	v_fmamk_f32 v95, v95, 0x3e0293ee, v66
	v_add_f32_e32 v86, v42, v86
	v_exp_f32_e32 v220, v95
	v_fmamk_f32 v95, v96, 0x3e0293ee, v66
	v_add_f32_e32 v86, v43, v86
	v_exp_f32_e32 v228, v95
	v_fmac_f32_e32 v66, 0x3e0293ee, v97
	v_add_f32_e32 v86, v44, v86
	v_exp_f32_e32 v229, v66
	v_add_f32_e32 v94, v45, v86
	v_add_f32_e32 v94, v220, v94
	v_add_f32_e32 v94, v228, v94
	v_add_f32_e32 v94, v229, v94
	v_add_f32_e32 v222, v5, v94
	v_add_u32_e32 v5, s64, v174
	v_add_u32_e32 v5, 0x4000, v5
	v_add_u32_e32 v66, v177, v5
	v_add_u32_e32 v67, v178, v5
	ds_read_b64_tr_b16 v[74:75], v66
	ds_read_b64_tr_b16 v[76:77], v66 offset:4096
	ds_read_b64_tr_b16 v[94:95], v66 offset:8192
	ds_read_b64_tr_b16 v[96:97], v66 offset:12288
	ds_read_b64_tr_b16 v[82:83], v67
	ds_read_b64_tr_b16 v[84:85], v67 offset:4096
	ds_read_b64_tr_b16 v[86:87], v67 offset:8192
	ds_read_b64_tr_b16 v[88:89], v67 offset:12288
	v_add_u32_e32 v38, v179, v5
	v_add_u32_e32 v39, v180, v5
	ds_read_b64_tr_b16 v[46:47], v38
	ds_read_b64_tr_b16 v[48:49], v38 offset:4096
	ds_read_b64_tr_b16 v[50:51], v38 offset:8192
	ds_read_b64_tr_b16 v[52:53], v38 offset:12288
	ds_read_b64_tr_b16 v[62:63], v39
	ds_read_b64_tr_b16 v[64:65], v39 offset:4096
	ds_read_b64_tr_b16 v[66:67], v39 offset:8192
	ds_read_b64_tr_b16 v[68:69], v39 offset:12288
	v_cvt_pk_f16_f32 v41, v92, v93
	v_cvt_pk_f16_f32 v40, v90, v91
	v_cvt_pk_f16_f32 v39, v100, v101
	v_cvt_pk_f16_f32 v38, v98, v99
	s_waitcnt lgkmcnt(8)
; #define LAS __attribute__((address_space(3)))
; #define AF_VWAIT(buf_, n_) asm volatile("s_waitcnt lgkmcnt(" #n_ ")" : "+v"(vr[buf_][0]), "+v"(vr[buf_][1]), "+v"(vr[buf_][2]), "+v"(vr[buf_][3]), "+v"(vr[buf_][4]), "+v"(vr[buf_][5]), "+v"(vr[buf_][6]), "+v"(vr[buf_][7]) :: "memory")
; template <bool a0, bool a1> __device__ __forceinline__ void af_pv(const LAS unsigned char* vbuf, unsigned vl0, int z, const half8 (&pf)[2][2], f32x4 (&o)[2][8]) {
;     const unsigned rb = (unsigned)(__UINTPTR_TYPE__)(vbuf + vl0);
;     s16x4 vr[2][8];
;     ...
;     AF_VLOAD(0, 0); AF_VLOAD(1, 2);
;     AF_VWAIT(0, 8); AF_VMMA(0, 0); AF_VLOAD(0, 4);
;     AF_VWAIT(1, 8); AF_VMMA(1, 2); AF_VLOAD(1, 6);
;     AF_VWAIT(0, 8); AF_VMMA(0, 4);
;     AF_VWAIT(1, 0); AF_VMMA(1, 6);
	v_cvt_pk_f16_f32 v219, v55, v56
	v_cvt_pk_f16_f32 v218, v61, v54
	v_mfma_f32_16x16x32_f16 v[134:137], v[74:77], v[38:41], v[134:137]
	v_cvt_pk_f16_f32 v217, v59, v60
	v_cvt_pk_f16_f32 v216, v73, v58
	v_cvt_pk_f16_f32 v227, v72, v2
	v_mfma_f32_16x16x32_f16 v[138:141], v[82:85], v[38:41], v[138:141]
	v_cvt_pk_f16_f32 v226, v70, v71
	v_cvt_pk_f16_f32 v225, v80, v81
	v_cvt_pk_f16_f32 v224, v78, v79
	v_mfma_f32_16x16x32_f16 v[102:105], v[74:77], v[216:219], v[102:105]
	v_mfma_f32_16x16x32_f16 v[106:109], v[82:85], v[216:219], v[106:109]
	v_mfma_f32_16x16x32_f16 v[98:101], v[94:97], v[224:227], v[134:137]
	s_nop 2
	v_cvt_pk_f16_f32 v137, v228, v229
	v_cvt_pk_f16_f32 v136, v45, v220
	v_cvt_pk_f16_f32 v135, v43, v44
	v_cvt_pk_f16_f32 v134, v57, v42
	v_mfma_f32_16x16x32_f16 v[90:93], v[86:89], v[224:227], v[138:141]
	s_nop 0
	v_mfma_f32_16x16x32_f16 v[94:97], v[94:97], v[134:137], v[102:105]
	v_mfma_f32_16x16x32_f16 v[86:89], v[86:89], v[134:137], v[106:109]
	v_add_u32_e32 v2, v181, v5
	v_add_u32_e32 v82, v182, v5
	ds_read_b64_tr_b16 v[58:59], v2
	ds_read_b64_tr_b16 v[60:61], v2 offset:4096
	ds_read_b64_tr_b16 v[102:103], v2 offset:8192
	ds_read_b64_tr_b16 v[104:105], v2 offset:12288
	ds_read_b64_tr_b16 v[138:139], v82
	ds_read_b64_tr_b16 v[140:141], v82 offset:4096
	ds_read_b64_tr_b16 v[106:107], v82 offset:8192
	ds_read_b64_tr_b16 v[108:109], v82 offset:12288
	s_waitcnt lgkmcnt(8)
	s_nop 0
	v_mfma_f32_16x16x32_f16 v[142:145], v[46:49], v[38:41], v[142:145]
	v_mfma_f32_16x16x32_f16 v[110:113], v[46:49], v[216:219], v[110:113]
	v_mfma_f32_16x16x32_f16 v[146:149], v[62:65], v[38:41], v[146:149]
	v_mfma_f32_16x16x32_f16 v[114:117], v[62:65], v[216:219], v[114:117]
	v_mfma_f32_16x16x32_f16 v[78:81], v[50:53], v[224:227], v[142:145]
	v_mfma_f32_16x16x32_f16 v[82:85], v[50:53], v[134:137], v[110:113]
	v_mfma_f32_16x16x32_f16 v[70:73], v[66:69], v[224:227], v[146:149]
	v_mfma_f32_16x16x32_f16 v[74:77], v[66:69], v[134:137], v[114:117]
	v_add_u32_e32 v2, v183, v5
	v_add_u32_e32 v5, v184, v5
	ds_read_b64_tr_b16 v[110:111], v2
	ds_read_b64_tr_b16 v[112:113], v2 offset:4096
	ds_read_b64_tr_b16 v[142:143], v2 offset:8192
	ds_read_b64_tr_b16 v[144:145], v2 offset:12288
	ds_read_b64_tr_b16 v[114:115], v5
	ds_read_b64_tr_b16 v[116:117], v5 offset:4096
	ds_read_b64_tr_b16 v[146:147], v5 offset:8192
	ds_read_b64_tr_b16 v[148:149], v5 offset:12288
	s_waitcnt lgkmcnt(8)
	s_nop 0
	v_mfma_f32_16x16x32_f16 v[150:153], v[58:61], v[38:41], v[150:153]
	v_mfma_f32_16x16x32_f16 v[118:121], v[58:61], v[216:219], v[118:121]
	v_mfma_f32_16x16x32_f16 v[58:61], v[102:105], v[224:227], v[150:153]
	v_mfma_f32_16x16x32_f16 v[154:157], v[138:141], v[38:41], v[154:157]
	v_mfma_f32_16x16x32_f16 v[150:153], v[138:141], v[216:219], v[122:125]
	v_mfma_f32_16x16x32_f16 v[66:69], v[102:105], v[134:137], v[118:121]
	v_mfma_f32_16x16x32_f16 v[54:57], v[106:109], v[224:227], v[154:157]
	v_mfma_f32_16x16x32_f16 v[62:65], v[106:109], v[134:137], v[150:153]
	s_waitcnt lgkmcnt(0)
	s_nop 0
	v_mfma_f32_16x16x32_f16 v[158:161], v[110:113], v[38:41], v[158:161]
	v_mfma_f32_16x16x32_f16 v[126:129], v[110:113], v[216:219], v[126:129]
	v_mfma_f32_16x16x32_f16 v[42:45], v[142:145], v[224:227], v[158:161]
	v_mfma_f32_16x16x32_f16 v[162:165], v[114:117], v[38:41], v[162:165]
	v_mfma_f32_16x16x32_f16 v[158:161], v[114:117], v[216:219], v[130:133]
	v_mfma_f32_16x16x32_f16 v[50:53], v[142:145], v[134:137], v[126:129]
	v_mfma_f32_16x16x32_f16 v[38:41], v[146:149], v[224:227], v[162:165]
	v_mfma_f32_16x16x32_f16 v[46:49], v[146:149], v[134:137], v[158:161]
	v_mov_b32_e32 v224, v4

; #define LAS __attribute__((address_space(3)))
; #define AF_WAITV(n) asm volatile("s_waitcnt vmcnt(" #n ")" ::: "memory")
; #define AF_BAR() do { __builtin_amdgcn_s_barrier(); asm volatile("" ::: "memory"); } while (0)
; __device__ __forceinline__ void attn_fast(const Ptrs& P, LAS unsigned char* lds, int G, int bid) {
;     ...
; #pragma unroll 1
;                 for (int i = 0; i < nt; ++i) {
;                     const int j = j_lo + i;
;                     if (i + 2 < nt) AF_WAITV(8); else if (i + 1 < nt) AF_WAITV(4); else AF_WAITV(0);
;                     AF_BAR();
;                     if (i + 3 < nt) AF_ISSUE((i + 3) & 3, KB, VB, DINP, 64 * (j + 3), true);
;                     int hi[2], lo[2]; bool act[2];
;                     const bool needmask = (j == qb) || (br == 2 && 64 * j <= 64 * qb + 63 - 512);
; #pragma unroll
;                     for (int ct = 0; ct < 2; ++ct) {
;                         if (br == 1) { const unsigned wd = SELM[(8 * w + 4 * ct + qi) * 4 + (j >> 5)]; const bool bit = (wd >> (j & 31)) & 1u;
;                             act[ct] = __ballot(bit) != 0ull; hi[ct] = bit ? tq[ct] : -1; lo[ct] = NEGBIG; }
;                         else { act[ct] = true; hi[ct] = tq[ct]; lo[ct] = tq[ct] - 512; }
;                     }
;                     const LAS unsigned char* stg = lds + (i & 3) * 32768;
;                     if (act[0] && act[1]) af_tile_online<true, true>(stg, kl, vl0, vz, qf, s, m, l, o, needmask, 64 * j, fq, hi, lo, SC);
;                     else if (act[0])      af_tile_online<true, false>(stg, kl, vl0, vz, qf, s, m, l, o, needmask, 64 * j, fq, hi, lo, SC);
;                     else if (act[1])      af_tile_online<false, true>(stg, kl, vl0, vz, qf, s, m, l, o, needmask, 64 * j, fq, hi, lo, SC);
;                 }
.Lu2_exit:
	s_nop 7
	v_mov_b64_e32 v[162:163], v[38:39]
	v_mov_b64_e32 v[158:159], v[42:43]
	v_mov_b64_e32 v[154:155], v[54:55]
	v_mov_b64_e32 v[150:151], v[58:59]
	v_mov_b64_e32 v[146:147], v[70:71]
	v_mov_b64_e32 v[142:143], v[78:79]
	v_mov_b64_e32 v[138:139], v[90:91]
	v_mov_b64_e32 v[134:135], v[98:99]
	v_mov_b64_e32 v[102:103], v[94:95]
	v_mov_b64_e32 v[106:107], v[86:87]
	v_mov_b64_e32 v[110:111], v[82:83]
	v_mov_b64_e32 v[114:115], v[74:75]
	v_mov_b64_e32 v[118:119], v[66:67]
	v_mov_b64_e32 v[122:123], v[62:63]
	v_mov_b64_e32 v[126:127], v[50:51]
	v_mov_b64_e32 v[130:131], v[46:47]
	v_mov_b64_e32 v[164:165], v[40:41]
	v_mov_b64_e32 v[160:161], v[44:45]
	v_mov_b64_e32 v[156:157], v[56:57]
	v_mov_b64_e32 v[152:153], v[60:61]
	v_mov_b64_e32 v[148:149], v[72:73]
	v_mov_b64_e32 v[144:145], v[80:81]
	v_mov_b64_e32 v[140:141], v[92:93]
	v_mov_b64_e32 v[136:137], v[100:101]
	v_mov_b64_e32 v[104:105], v[96:97]
	v_mov_b64_e32 v[108:109], v[88:89]
	v_mov_b64_e32 v[112:113], v[84:85]
	v_mov_b64_e32 v[116:117], v[76:77]
	v_mov_b64_e32 v[120:121], v[68:69]
	v_mov_b64_e32 v[124:125], v[64:65]
	v_mov_b64_e32 v[128:129], v[52:53]
	v_mov_b64_e32 v[132:133], v[48:49]
	s_branch .LBB0_623
